# GEMM K loop: second K half cut into row groups of 3,3(4),5,5 so the groups on both sides of the step barrier are the largest
# baseline (speedup 1.0000x reference)
.Lg2_ff2_loop17:
	s_add_u32 s58, s58, 0x800
	s_addc_u32 s59, s59, 0
	global_load_dwordx4 v[200:203], v160, s[58:59] offset:0
	global_load_dwordx4 v[204:207], v160, s[58:59] offset:1024
	global_load_dwordx4 v[208:211], v161, s[58:59] offset:0
	global_load_dwordx4 v[240:243], v161, s[58:59] offset:1024
	ds_read_b128 v[164:167], v156 offset:8192
	ds_read_b128 v[168:171], v156 offset:10240
	ds_read_b128 v[172:175], v156 offset:12288
	ds_read_b128 v[176:179], v156 offset:14336
	s_waitcnt lgkmcnt(4)
	v_mfma_f32_16x16x32_bf16 v[0:3], v[184:187], v[136:139], v[0:3]
	v_mfma_f32_16x16x32_bf16 v[4:7], v[192:195], v[136:139], v[4:7]
	v_mfma_f32_16x16x32_bf16 v[8:11], v[184:187], v[140:143], v[8:11]
	v_mfma_f32_16x16x32_bf16 v[12:15], v[192:195], v[140:143], v[12:15]
	v_mfma_f32_16x16x32_bf16 v[16:19], v[184:187], v[144:147], v[16:19]
	v_mfma_f32_16x16x32_bf16 v[20:23], v[192:195], v[144:147], v[20:23]
	v_mfma_f32_16x16x32_bf16 v[24:27], v[184:187], v[148:151], v[24:27]
	v_mfma_f32_16x16x32_bf16 v[28:31], v[192:195], v[148:151], v[28:31]
	ds_read_b128 v[136:139], v156 offset:16384
	ds_read_b128 v[140:143], v156 offset:18432
	ds_read_b128 v[144:147], v156 offset:20480
	ds_read_b128 v[148:151], v156 offset:22528
	s_waitcnt lgkmcnt(4)
	v_mfma_f32_16x16x32_bf16 v[32:35], v[184:187], v[164:167], v[32:35]
	v_mfma_f32_16x16x32_bf16 v[36:39], v[192:195], v[164:167], v[36:39]
	v_mfma_f32_16x16x32_bf16 v[40:43], v[184:187], v[168:171], v[40:43]
	v_mfma_f32_16x16x32_bf16 v[44:47], v[192:195], v[168:171], v[44:47]
	v_mfma_f32_16x16x32_bf16 v[48:51], v[184:187], v[172:175], v[48:51]
	v_mfma_f32_16x16x32_bf16 v[52:55], v[192:195], v[172:175], v[52:55]
	v_mfma_f32_16x16x32_bf16 v[56:59], v[184:187], v[176:179], v[56:59]
	v_mfma_f32_16x16x32_bf16 v[60:63], v[192:195], v[176:179], v[60:63]
	ds_read_b128 v[164:167], v156 offset:24576
	ds_read_b128 v[168:171], v156 offset:26624
	ds_read_b128 v[172:175], v156 offset:28672
	ds_read_b128 v[176:179], v156 offset:30720
	ds_read_b128 v[180:183], v156 offset:32768
	s_waitcnt lgkmcnt(5)
	v_mfma_f32_16x16x32_bf16 v[64:67], v[184:187], v[136:139], v[64:67]
	v_mfma_f32_16x16x32_bf16 v[68:71], v[192:195], v[136:139], v[68:71]
	v_mfma_f32_16x16x32_bf16 v[72:75], v[184:187], v[140:143], v[72:75]
	v_mfma_f32_16x16x32_bf16 v[76:79], v[192:195], v[140:143], v[76:79]
	v_mfma_f32_16x16x32_bf16 v[80:83], v[184:187], v[144:147], v[80:83]
	v_mfma_f32_16x16x32_bf16 v[84:87], v[192:195], v[144:147], v[84:87]
	v_mfma_f32_16x16x32_bf16 v[88:91], v[184:187], v[148:151], v[88:91]
	v_mfma_f32_16x16x32_bf16 v[92:95], v[192:195], v[148:151], v[92:95]
	ds_read_b128 v[136:139], v157 offset:0
	ds_read_b128 v[140:143], v157 offset:2048
	ds_read_b128 v[144:147], v157 offset:4096
	s_waitcnt lgkmcnt(3)
	v_mfma_f32_16x16x32_bf16 v[96:99], v[184:187], v[164:167], v[96:99]
	v_mfma_f32_16x16x32_bf16 v[100:103], v[192:195], v[164:167], v[100:103]
	v_mfma_f32_16x16x32_bf16 v[104:107], v[184:187], v[168:171], v[104:107]
	v_mfma_f32_16x16x32_bf16 v[108:111], v[192:195], v[168:171], v[108:111]
	v_mfma_f32_16x16x32_bf16 v[112:115], v[184:187], v[172:175], v[112:115]
	v_mfma_f32_16x16x32_bf16 v[116:119], v[192:195], v[172:175], v[116:119]
	v_mfma_f32_16x16x32_bf16 v[120:123], v[184:187], v[176:179], v[120:123]
	v_mfma_f32_16x16x32_bf16 v[124:127], v[192:195], v[176:179], v[124:127]
	v_mfma_f32_16x16x32_bf16 v[128:131], v[184:187], v[180:183], v[128:131]
	v_mfma_f32_16x16x32_bf16 v[132:135], v[192:195], v[180:183], v[132:135]
	ds_read_b128 v[164:167], v157 offset:6144
	ds_read_b128 v[168:171], v157 offset:8192
	ds_read_b128 v[172:175], v157 offset:10240
	ds_read_b128 v[176:179], v157 offset:12288
	s_waitcnt lgkmcnt(4)
	v_mfma_f32_16x16x32_bf16 v[0:3], v[188:191], v[136:139], v[0:3]
	v_mfma_f32_16x16x32_bf16 v[4:7], v[196:199], v[136:139], v[4:7]
	v_mfma_f32_16x16x32_bf16 v[8:11], v[188:191], v[140:143], v[8:11]
	v_mfma_f32_16x16x32_bf16 v[12:15], v[196:199], v[140:143], v[12:15]
	v_mfma_f32_16x16x32_bf16 v[16:19], v[188:191], v[144:147], v[16:19]
	v_mfma_f32_16x16x32_bf16 v[20:23], v[196:199], v[144:147], v[20:23]
	ds_read_b128 v[136:139], v157 offset:14336
	ds_read_b128 v[140:143], v157 offset:16384
	ds_read_b128 v[144:147], v157 offset:18432
	ds_read_b128 v[148:151], v157 offset:20480
	ds_read_b128 v[152:155], v157 offset:22528
	s_waitcnt lgkmcnt(5)
	v_mfma_f32_16x16x32_bf16 v[24:27], v[188:191], v[164:167], v[24:27]
	v_mfma_f32_16x16x32_bf16 v[28:31], v[196:199], v[164:167], v[28:31]
	v_mfma_f32_16x16x32_bf16 v[32:35], v[188:191], v[168:171], v[32:35]
	v_mfma_f32_16x16x32_bf16 v[36:39], v[196:199], v[168:171], v[36:39]
	v_mfma_f32_16x16x32_bf16 v[40:43], v[188:191], v[172:175], v[40:43]
	v_mfma_f32_16x16x32_bf16 v[44:47], v[196:199], v[172:175], v[44:47]
	v_mfma_f32_16x16x32_bf16 v[48:51], v[188:191], v[176:179], v[48:51]
	v_mfma_f32_16x16x32_bf16 v[52:55], v[196:199], v[176:179], v[52:55]
	ds_read_b128 v[164:167], v157 offset:24576
	ds_read_b128 v[168:171], v157 offset:26624
	ds_read_b128 v[172:175], v157 offset:28672
	ds_read_b128 v[176:179], v157 offset:30720
	ds_read_b128 v[180:183], v157 offset:32768
	s_waitcnt lgkmcnt(5)
	v_mfma_f32_16x16x32_bf16 v[56:59], v[188:191], v[136:139], v[56:59]
	v_mfma_f32_16x16x32_bf16 v[60:63], v[196:199], v[136:139], v[60:63]
	v_mfma_f32_16x16x32_bf16 v[64:67], v[188:191], v[140:143], v[64:67]
	v_mfma_f32_16x16x32_bf16 v[68:71], v[196:199], v[140:143], v[68:71]
	v_mfma_f32_16x16x32_bf16 v[72:75], v[188:191], v[144:147], v[72:75]
	v_mfma_f32_16x16x32_bf16 v[76:79], v[196:199], v[144:147], v[76:79]
	v_mfma_f32_16x16x32_bf16 v[80:83], v[188:191], v[148:151], v[80:83]
	v_mfma_f32_16x16x32_bf16 v[84:87], v[196:199], v[148:151], v[84:87]
	v_mfma_f32_16x16x32_bf16 v[88:91], v[188:191], v[152:155], v[88:91]
	v_mfma_f32_16x16x32_bf16 v[92:95], v[196:199], v[152:155], v[92:95]
	s_waitcnt vmcnt(0) lgkmcnt(0)
	s_barrier
	s_cmp_ge_u32 s63, 62
	s_cbranch_scc1 .Lg2_ff2_nd17_0
	s_add_u32 s56, s56, 0x80
	s_addc_u32 s57, s57, 0
	s_add_u32 m0, s62, 0x0
	s_add_u32 s4, s56, 0x0
	s_addc_u32 s5, s57, 0
	global_load_lds_dwordx4 v162, s[4:5]
	s_add_u32 m0, s62, 0x1000
	s_add_u32 s4, s56, 0x40000
	s_addc_u32 s5, s57, 0
	global_load_lds_dwordx4 v162, s[4:5]
	s_add_u32 m0, s62, 0x2000
	s_add_u32 s4, s56, 0x80000
	s_addc_u32 s5, s57, 0
	global_load_lds_dwordx4 v162, s[4:5]
	s_add_u32 m0, s62, 0x3000
	s_add_u32 s4, s56, 0xc0000
	s_addc_u32 s5, s57, 0
	global_load_lds_dwordx4 v162, s[4:5]
	s_add_u32 m0, s62, 0x4000
	s_add_u32 s4, s56, 0x100000
	s_addc_u32 s5, s57, 0
	global_load_lds_dwordx4 v162, s[4:5]
	s_add_u32 m0, s62, 0x5000
	s_add_u32 s4, s56, 0x140000
	s_addc_u32 s5, s57, 0
	global_load_lds_dwordx4 v162, s[4:5]
	s_add_u32 m0, s62, 0x6000
	s_add_u32 s4, s56, 0x180000
	s_addc_u32 s5, s57, 0
	global_load_lds_dwordx4 v162, s[4:5]
	s_add_u32 m0, s62, 0x7000
	s_add_u32 s4, s56, 0x1c0000
	s_addc_u32 s5, s57, 0
	global_load_lds_dwordx4 v162, s[4:5]
	s_cmp_gt_u32 s70, 1
	s_cbranch_scc1 .Lg2_ff2_nodma_2
	s_add_u32 m0, s62, 0x8000
	s_add_u32 s4, s56, 0x200000
	s_addc_u32 s5, s57, 0
	global_load_lds_dwordx4 v162, s[4:5]

.Lg2_ff2_nb17_1:
	ds_read_b128 v[164:167], v158 offset:8192
	ds_read_b128 v[168:171], v158 offset:10240
	ds_read_b128 v[172:175], v158 offset:12288
	ds_read_b128 v[176:179], v158 offset:14336
	s_waitcnt lgkmcnt(4)
	v_mfma_f32_16x16x32_bf16 v[0:3], v[200:203], v[136:139], v[0:3]
	v_mfma_f32_16x16x32_bf16 v[4:7], v[208:211], v[136:139], v[4:7]
	v_mfma_f32_16x16x32_bf16 v[8:11], v[200:203], v[140:143], v[8:11]
	v_mfma_f32_16x16x32_bf16 v[12:15], v[208:211], v[140:143], v[12:15]
	v_mfma_f32_16x16x32_bf16 v[16:19], v[200:203], v[144:147], v[16:19]
	v_mfma_f32_16x16x32_bf16 v[20:23], v[208:211], v[144:147], v[20:23]
	v_mfma_f32_16x16x32_bf16 v[24:27], v[200:203], v[148:151], v[24:27]
	v_mfma_f32_16x16x32_bf16 v[28:31], v[208:211], v[148:151], v[28:31]
	ds_read_b128 v[136:139], v158 offset:16384
	ds_read_b128 v[140:143], v158 offset:18432
	ds_read_b128 v[144:147], v158 offset:20480
	ds_read_b128 v[148:151], v158 offset:22528
	s_waitcnt lgkmcnt(4)
	v_mfma_f32_16x16x32_bf16 v[32:35], v[200:203], v[164:167], v[32:35]
	v_mfma_f32_16x16x32_bf16 v[36:39], v[208:211], v[164:167], v[36:39]
	v_mfma_f32_16x16x32_bf16 v[40:43], v[200:203], v[168:171], v[40:43]
	v_mfma_f32_16x16x32_bf16 v[44:47], v[208:211], v[168:171], v[44:47]
	v_mfma_f32_16x16x32_bf16 v[48:51], v[200:203], v[172:175], v[48:51]
	v_mfma_f32_16x16x32_bf16 v[52:55], v[208:211], v[172:175], v[52:55]
	v_mfma_f32_16x16x32_bf16 v[56:59], v[200:203], v[176:179], v[56:59]
	v_mfma_f32_16x16x32_bf16 v[60:63], v[208:211], v[176:179], v[60:63]
	ds_read_b128 v[164:167], v158 offset:24576
	ds_read_b128 v[168:171], v158 offset:26624
	ds_read_b128 v[172:175], v158 offset:28672
	ds_read_b128 v[176:179], v158 offset:30720
	ds_read_b128 v[180:183], v158 offset:32768
	s_waitcnt lgkmcnt(5)
	v_mfma_f32_16x16x32_bf16 v[64:67], v[200:203], v[136:139], v[64:67]
	v_mfma_f32_16x16x32_bf16 v[68:71], v[208:211], v[136:139], v[68:71]
	v_mfma_f32_16x16x32_bf16 v[72:75], v[200:203], v[140:143], v[72:75]
	v_mfma_f32_16x16x32_bf16 v[76:79], v[208:211], v[140:143], v[76:79]
	v_mfma_f32_16x16x32_bf16 v[80:83], v[200:203], v[144:147], v[80:83]
	v_mfma_f32_16x16x32_bf16 v[84:87], v[208:211], v[144:147], v[84:87]
	v_mfma_f32_16x16x32_bf16 v[88:91], v[200:203], v[148:151], v[88:91]
	v_mfma_f32_16x16x32_bf16 v[92:95], v[208:211], v[148:151], v[92:95]
	ds_read_b128 v[136:139], v159 offset:0
	ds_read_b128 v[140:143], v159 offset:2048
	ds_read_b128 v[144:147], v159 offset:4096
	s_waitcnt lgkmcnt(3)
	v_mfma_f32_16x16x32_bf16 v[96:99], v[200:203], v[164:167], v[96:99]
	v_mfma_f32_16x16x32_bf16 v[100:103], v[208:211], v[164:167], v[100:103]
	v_mfma_f32_16x16x32_bf16 v[104:107], v[200:203], v[168:171], v[104:107]
	v_mfma_f32_16x16x32_bf16 v[108:111], v[208:211], v[168:171], v[108:111]
	v_mfma_f32_16x16x32_bf16 v[112:115], v[200:203], v[172:175], v[112:115]
	v_mfma_f32_16x16x32_bf16 v[116:119], v[208:211], v[172:175], v[116:119]
	v_mfma_f32_16x16x32_bf16 v[120:123], v[200:203], v[176:179], v[120:123]
	v_mfma_f32_16x16x32_bf16 v[124:127], v[208:211], v[176:179], v[124:127]
	v_mfma_f32_16x16x32_bf16 v[128:131], v[200:203], v[180:183], v[128:131]
	v_mfma_f32_16x16x32_bf16 v[132:135], v[208:211], v[180:183], v[132:135]
	ds_read_b128 v[164:167], v159 offset:6144
	ds_read_b128 v[168:171], v159 offset:8192
	ds_read_b128 v[172:175], v159 offset:10240
	ds_read_b128 v[176:179], v159 offset:12288
	s_waitcnt lgkmcnt(4)
	v_mfma_f32_16x16x32_bf16 v[0:3], v[204:207], v[136:139], v[0:3]
	v_mfma_f32_16x16x32_bf16 v[4:7], v[240:243], v[136:139], v[4:7]
	v_mfma_f32_16x16x32_bf16 v[8:11], v[204:207], v[140:143], v[8:11]
	v_mfma_f32_16x16x32_bf16 v[12:15], v[240:243], v[140:143], v[12:15]
	v_mfma_f32_16x16x32_bf16 v[16:19], v[204:207], v[144:147], v[16:19]
	v_mfma_f32_16x16x32_bf16 v[20:23], v[240:243], v[144:147], v[20:23]
	ds_read_b128 v[136:139], v159 offset:14336
	ds_read_b128 v[140:143], v159 offset:16384
	ds_read_b128 v[144:147], v159 offset:18432
	ds_read_b128 v[148:151], v159 offset:20480
	ds_read_b128 v[152:155], v159 offset:22528
	s_waitcnt lgkmcnt(5)
	v_mfma_f32_16x16x32_bf16 v[24:27], v[204:207], v[164:167], v[24:27]
	v_mfma_f32_16x16x32_bf16 v[28:31], v[240:243], v[164:167], v[28:31]
	v_mfma_f32_16x16x32_bf16 v[32:35], v[204:207], v[168:171], v[32:35]
	v_mfma_f32_16x16x32_bf16 v[36:39], v[240:243], v[168:171], v[36:39]
	v_mfma_f32_16x16x32_bf16 v[40:43], v[204:207], v[172:175], v[40:43]
	v_mfma_f32_16x16x32_bf16 v[44:47], v[240:243], v[172:175], v[44:47]
	v_mfma_f32_16x16x32_bf16 v[48:51], v[204:207], v[176:179], v[48:51]
	v_mfma_f32_16x16x32_bf16 v[52:55], v[240:243], v[176:179], v[52:55]
	ds_read_b128 v[164:167], v159 offset:24576
	ds_read_b128 v[168:171], v159 offset:26624
	ds_read_b128 v[172:175], v159 offset:28672
	ds_read_b128 v[176:179], v159 offset:30720
	ds_read_b128 v[180:183], v159 offset:32768
	s_waitcnt lgkmcnt(5)
	v_mfma_f32_16x16x32_bf16 v[56:59], v[204:207], v[136:139], v[56:59]
	v_mfma_f32_16x16x32_bf16 v[60:63], v[240:243], v[136:139], v[60:63]
	v_mfma_f32_16x16x32_bf16 v[64:67], v[204:207], v[140:143], v[64:67]
	v_mfma_f32_16x16x32_bf16 v[68:71], v[240:243], v[140:143], v[68:71]
	v_mfma_f32_16x16x32_bf16 v[72:75], v[204:207], v[144:147], v[72:75]
	v_mfma_f32_16x16x32_bf16 v[76:79], v[240:243], v[144:147], v[76:79]
	v_mfma_f32_16x16x32_bf16 v[80:83], v[204:207], v[148:151], v[80:83]
	v_mfma_f32_16x16x32_bf16 v[84:87], v[240:243], v[148:151], v[84:87]
	v_mfma_f32_16x16x32_bf16 v[88:91], v[204:207], v[152:155], v[88:91]
	v_mfma_f32_16x16x32_bf16 v[92:95], v[240:243], v[152:155], v[92:95]
	s_waitcnt vmcnt(0) lgkmcnt(0)
	s_barrier
	s_cmp_ge_u32 s63, 62
	s_cbranch_scc1 .Lg2_ff2_nd17_1
	s_add_u32 s56, s56, 0x80
	s_addc_u32 s57, s57, 0
	s_add_u32 m0, s62, 0x8800
	s_add_u32 s4, s56, 0x0
	s_addc_u32 s5, s57, 0
	global_load_lds_dwordx4 v162, s[4:5]
	s_add_u32 m0, s62, 0x9800
	s_add_u32 s4, s56, 0x40000
	s_addc_u32 s5, s57, 0
	global_load_lds_dwordx4 v162, s[4:5]
	s_add_u32 m0, s62, 0xa800
	s_add_u32 s4, s56, 0x80000
	s_addc_u32 s5, s57, 0
	global_load_lds_dwordx4 v162, s[4:5]
	s_add_u32 m0, s62, 0xb800
	s_add_u32 s4, s56, 0xc0000
	s_addc_u32 s5, s57, 0
	global_load_lds_dwordx4 v162, s[4:5]
	s_add_u32 m0, s62, 0xc800
	s_add_u32 s4, s56, 0x100000
	s_addc_u32 s5, s57, 0
	global_load_lds_dwordx4 v162, s[4:5]
	s_add_u32 m0, s62, 0xd800
	s_add_u32 s4, s56, 0x140000
	s_addc_u32 s5, s57, 0
	global_load_lds_dwordx4 v162, s[4:5]
	s_add_u32 m0, s62, 0xe800
	s_add_u32 s4, s56, 0x180000
	s_addc_u32 s5, s57, 0
	global_load_lds_dwordx4 v162, s[4:5]
	s_add_u32 m0, s62, 0xf800
	s_add_u32 s4, s56, 0x1c0000
	s_addc_u32 s5, s57, 0
	global_load_lds_dwordx4 v162, s[4:5]
	s_cmp_gt_u32 s70, 1
	s_cbranch_scc1 .Lg2_ff2_nodma_3
	s_add_u32 m0, s62, 0x10800
	s_add_u32 s4, s56, 0x200000
	s_addc_u32 s5, s57, 0
	global_load_lds_dwordx4 v162, s[4:5]

.Lg2_ff2_loop16:
	s_add_u32 s58, s58, 0x800
	s_addc_u32 s59, s59, 0
	global_load_dwordx4 v[200:203], v160, s[58:59] offset:0
	global_load_dwordx4 v[204:207], v160, s[58:59] offset:1024
	global_load_dwordx4 v[208:211], v161, s[58:59] offset:0
	global_load_dwordx4 v[240:243], v161, s[58:59] offset:1024
	ds_read_b128 v[164:167], v156 offset:8192
	ds_read_b128 v[168:171], v156 offset:10240
	ds_read_b128 v[172:175], v156 offset:12288
	ds_read_b128 v[176:179], v156 offset:14336
	s_waitcnt lgkmcnt(4)
	v_mfma_f32_16x16x32_bf16 v[0:3], v[184:187], v[136:139], v[0:3]
	v_mfma_f32_16x16x32_bf16 v[4:7], v[192:195], v[136:139], v[4:7]
	v_mfma_f32_16x16x32_bf16 v[8:11], v[184:187], v[140:143], v[8:11]
	v_mfma_f32_16x16x32_bf16 v[12:15], v[192:195], v[140:143], v[12:15]
	v_mfma_f32_16x16x32_bf16 v[16:19], v[184:187], v[144:147], v[16:19]
	v_mfma_f32_16x16x32_bf16 v[20:23], v[192:195], v[144:147], v[20:23]
	v_mfma_f32_16x16x32_bf16 v[24:27], v[184:187], v[148:151], v[24:27]
	v_mfma_f32_16x16x32_bf16 v[28:31], v[192:195], v[148:151], v[28:31]
	ds_read_b128 v[136:139], v156 offset:16384
	ds_read_b128 v[140:143], v156 offset:18432
	ds_read_b128 v[144:147], v156 offset:20480
	ds_read_b128 v[148:151], v156 offset:22528
	s_waitcnt lgkmcnt(4)
	v_mfma_f32_16x16x32_bf16 v[32:35], v[184:187], v[164:167], v[32:35]
	v_mfma_f32_16x16x32_bf16 v[36:39], v[192:195], v[164:167], v[36:39]
	v_mfma_f32_16x16x32_bf16 v[40:43], v[184:187], v[168:171], v[40:43]
	v_mfma_f32_16x16x32_bf16 v[44:47], v[192:195], v[168:171], v[44:47]
	v_mfma_f32_16x16x32_bf16 v[48:51], v[184:187], v[172:175], v[48:51]
	v_mfma_f32_16x16x32_bf16 v[52:55], v[192:195], v[172:175], v[52:55]
	v_mfma_f32_16x16x32_bf16 v[56:59], v[184:187], v[176:179], v[56:59]
	v_mfma_f32_16x16x32_bf16 v[60:63], v[192:195], v[176:179], v[60:63]
	ds_read_b128 v[164:167], v156 offset:24576
	ds_read_b128 v[168:171], v156 offset:26624
	ds_read_b128 v[172:175], v156 offset:28672
	ds_read_b128 v[176:179], v156 offset:30720
	s_waitcnt lgkmcnt(4)
	v_mfma_f32_16x16x32_bf16 v[64:67], v[184:187], v[136:139], v[64:67]
	v_mfma_f32_16x16x32_bf16 v[68:71], v[192:195], v[136:139], v[68:71]
	v_mfma_f32_16x16x32_bf16 v[72:75], v[184:187], v[140:143], v[72:75]
	v_mfma_f32_16x16x32_bf16 v[76:79], v[192:195], v[140:143], v[76:79]
	v_mfma_f32_16x16x32_bf16 v[80:83], v[184:187], v[144:147], v[80:83]
	v_mfma_f32_16x16x32_bf16 v[84:87], v[192:195], v[144:147], v[84:87]
	v_mfma_f32_16x16x32_bf16 v[88:91], v[184:187], v[148:151], v[88:91]
	v_mfma_f32_16x16x32_bf16 v[92:95], v[192:195], v[148:151], v[92:95]
	ds_read_b128 v[136:139], v157 offset:0
	ds_read_b128 v[140:143], v157 offset:2048
	ds_read_b128 v[144:147], v157 offset:4096
	s_waitcnt lgkmcnt(3)
	v_mfma_f32_16x16x32_bf16 v[96:99], v[184:187], v[164:167], v[96:99]
	v_mfma_f32_16x16x32_bf16 v[100:103], v[192:195], v[164:167], v[100:103]
	v_mfma_f32_16x16x32_bf16 v[104:107], v[184:187], v[168:171], v[104:107]
	v_mfma_f32_16x16x32_bf16 v[108:111], v[192:195], v[168:171], v[108:111]
	v_mfma_f32_16x16x32_bf16 v[112:115], v[184:187], v[172:175], v[112:115]
	v_mfma_f32_16x16x32_bf16 v[116:119], v[192:195], v[172:175], v[116:119]
	v_mfma_f32_16x16x32_bf16 v[120:123], v[184:187], v[176:179], v[120:123]
	v_mfma_f32_16x16x32_bf16 v[124:127], v[192:195], v[176:179], v[124:127]
	ds_read_b128 v[164:167], v157 offset:6144
	ds_read_b128 v[168:171], v157 offset:8192
	ds_read_b128 v[172:175], v157 offset:10240
	s_waitcnt lgkmcnt(3)
	v_mfma_f32_16x16x32_bf16 v[0:3], v[188:191], v[136:139], v[0:3]
	v_mfma_f32_16x16x32_bf16 v[4:7], v[196:199], v[136:139], v[4:7]
	v_mfma_f32_16x16x32_bf16 v[8:11], v[188:191], v[140:143], v[8:11]
	v_mfma_f32_16x16x32_bf16 v[12:15], v[196:199], v[140:143], v[12:15]
	v_mfma_f32_16x16x32_bf16 v[16:19], v[188:191], v[144:147], v[16:19]
	v_mfma_f32_16x16x32_bf16 v[20:23], v[196:199], v[144:147], v[20:23]
	ds_read_b128 v[136:139], v157 offset:12288
	ds_read_b128 v[140:143], v157 offset:14336
	ds_read_b128 v[144:147], v157 offset:16384
	ds_read_b128 v[148:151], v157 offset:18432
	ds_read_b128 v[152:155], v157 offset:20480
	s_waitcnt lgkmcnt(5)
	v_mfma_f32_16x16x32_bf16 v[24:27], v[188:191], v[164:167], v[24:27]
	v_mfma_f32_16x16x32_bf16 v[28:31], v[196:199], v[164:167], v[28:31]
	v_mfma_f32_16x16x32_bf16 v[32:35], v[188:191], v[168:171], v[32:35]
	v_mfma_f32_16x16x32_bf16 v[36:39], v[196:199], v[168:171], v[36:39]
	v_mfma_f32_16x16x32_bf16 v[40:43], v[188:191], v[172:175], v[40:43]
	v_mfma_f32_16x16x32_bf16 v[44:47], v[196:199], v[172:175], v[44:47]
	ds_read_b128 v[164:167], v157 offset:22528
	ds_read_b128 v[168:171], v157 offset:24576
	ds_read_b128 v[172:175], v157 offset:26624
	ds_read_b128 v[176:179], v157 offset:28672
	ds_read_b128 v[180:183], v157 offset:30720
	s_waitcnt lgkmcnt(5)
	v_mfma_f32_16x16x32_bf16 v[48:51], v[188:191], v[136:139], v[48:51]
	v_mfma_f32_16x16x32_bf16 v[52:55], v[196:199], v[136:139], v[52:55]
	v_mfma_f32_16x16x32_bf16 v[56:59], v[188:191], v[140:143], v[56:59]
	v_mfma_f32_16x16x32_bf16 v[60:63], v[196:199], v[140:143], v[60:63]
	v_mfma_f32_16x16x32_bf16 v[64:67], v[188:191], v[144:147], v[64:67]
	v_mfma_f32_16x16x32_bf16 v[68:71], v[196:199], v[144:147], v[68:71]
	v_mfma_f32_16x16x32_bf16 v[72:75], v[188:191], v[148:151], v[72:75]
	v_mfma_f32_16x16x32_bf16 v[76:79], v[196:199], v[148:151], v[76:79]
	v_mfma_f32_16x16x32_bf16 v[80:83], v[188:191], v[152:155], v[80:83]
	v_mfma_f32_16x16x32_bf16 v[84:87], v[196:199], v[152:155], v[84:87]
	s_waitcnt vmcnt(0) lgkmcnt(0)
	s_barrier
	s_cmp_ge_u32 s63, 62
	s_cbranch_scc1 .Lg2_ff2_nd16_0
	s_add_u32 s56, s56, 0x80
	s_addc_u32 s57, s57, 0
	s_add_u32 m0, s62, 0x0
	s_add_u32 s4, s56, 0x0
	s_addc_u32 s5, s57, 0
	global_load_lds_dwordx4 v162, s[4:5]
	s_add_u32 m0, s62, 0x1000
	s_add_u32 s4, s56, 0x40000
	s_addc_u32 s5, s57, 0
	global_load_lds_dwordx4 v162, s[4:5]
	s_add_u32 m0, s62, 0x2000
	s_add_u32 s4, s56, 0x80000
	s_addc_u32 s5, s57, 0
	global_load_lds_dwordx4 v162, s[4:5]
	s_add_u32 m0, s62, 0x3000
	s_add_u32 s4, s56, 0xc0000
	s_addc_u32 s5, s57, 0
	global_load_lds_dwordx4 v162, s[4:5]
	s_add_u32 m0, s62, 0x4000
	s_add_u32 s4, s56, 0x100000
	s_addc_u32 s5, s57, 0
	global_load_lds_dwordx4 v162, s[4:5]
	s_add_u32 m0, s62, 0x5000
	s_add_u32 s4, s56, 0x140000
	s_addc_u32 s5, s57, 0
	global_load_lds_dwordx4 v162, s[4:5]
	s_add_u32 m0, s62, 0x6000
	s_add_u32 s4, s56, 0x180000
	s_addc_u32 s5, s57, 0
	global_load_lds_dwordx4 v162, s[4:5]
	s_add_u32 m0, s62, 0x7000
	s_add_u32 s4, s56, 0x1c0000
	s_addc_u32 s5, s57, 0
	global_load_lds_dwordx4 v162, s[4:5]
.Lg2_ff2_nd16_0:
	ds_read_b128 v[136:139], v158 offset:0
	ds_read_b128 v[140:143], v158 offset:2048
	ds_read_b128 v[144:147], v158 offset:4096
	ds_read_b128 v[148:151], v158 offset:6144
	v_mfma_f32_16x16x32_bf16 v[88:91], v[188:191], v[164:167], v[88:91]
	v_mfma_f32_16x16x32_bf16 v[92:95], v[196:199], v[164:167], v[92:95]
	v_mfma_f32_16x16x32_bf16 v[96:99], v[188:191], v[168:171], v[96:99]
	v_mfma_f32_16x16x32_bf16 v[100:103], v[196:199], v[168:171], v[100:103]
	v_mfma_f32_16x16x32_bf16 v[104:107], v[188:191], v[172:175], v[104:107]
	v_mfma_f32_16x16x32_bf16 v[108:111], v[196:199], v[172:175], v[108:111]
	v_mfma_f32_16x16x32_bf16 v[112:115], v[188:191], v[176:179], v[112:115]
	v_mfma_f32_16x16x32_bf16 v[116:119], v[196:199], v[176:179], v[116:119]
	v_mfma_f32_16x16x32_bf16 v[120:123], v[188:191], v[180:183], v[120:123]
	v_mfma_f32_16x16x32_bf16 v[124:127], v[196:199], v[180:183], v[124:127]
	s_cmp_ge_u32 s63, 62
	s_cbranch_scc1 .Lg2_ff2_nb16_1
	s_add_u32 s58, s58, 0x800
	s_addc_u32 s59, s59, 0
	global_load_dwordx4 v[184:187], v160, s[58:59] offset:0
	global_load_dwordx4 v[188:191], v160, s[58:59] offset:1024
	global_load_dwordx4 v[192:195], v161, s[58:59] offset:0
	global_load_dwordx4 v[196:199], v161, s[58:59] offset:1024
.Lg2_ff2_nb16_1:
	ds_read_b128 v[164:167], v158 offset:8192
	ds_read_b128 v[168:171], v158 offset:10240
	ds_read_b128 v[172:175], v158 offset:12288
	ds_read_b128 v[176:179], v158 offset:14336
	s_waitcnt lgkmcnt(4)
	v_mfma_f32_16x16x32_bf16 v[0:3], v[200:203], v[136:139], v[0:3]
	v_mfma_f32_16x16x32_bf16 v[4:7], v[208:211], v[136:139], v[4:7]
	v_mfma_f32_16x16x32_bf16 v[8:11], v[200:203], v[140:143], v[8:11]
	v_mfma_f32_16x16x32_bf16 v[12:15], v[208:211], v[140:143], v[12:15]
	v_mfma_f32_16x16x32_bf16 v[16:19], v[200:203], v[144:147], v[16:19]
	v_mfma_f32_16x16x32_bf16 v[20:23], v[208:211], v[144:147], v[20:23]
	v_mfma_f32_16x16x32_bf16 v[24:27], v[200:203], v[148:151], v[24:27]
	v_mfma_f32_16x16x32_bf16 v[28:31], v[208:211], v[148:151], v[28:31]
	ds_read_b128 v[136:139], v158 offset:16384
	ds_read_b128 v[140:143], v158 offset:18432
	ds_read_b128 v[144:147], v158 offset:20480
	ds_read_b128 v[148:151], v158 offset:22528
	s_waitcnt lgkmcnt(4)
	v_mfma_f32_16x16x32_bf16 v[32:35], v[200:203], v[164:167], v[32:35]
	v_mfma_f32_16x16x32_bf16 v[36:39], v[208:211], v[164:167], v[36:39]
	v_mfma_f32_16x16x32_bf16 v[40:43], v[200:203], v[168:171], v[40:43]
	v_mfma_f32_16x16x32_bf16 v[44:47], v[208:211], v[168:171], v[44:47]
	v_mfma_f32_16x16x32_bf16 v[48:51], v[200:203], v[172:175], v[48:51]
	v_mfma_f32_16x16x32_bf16 v[52:55], v[208:211], v[172:175], v[52:55]
	v_mfma_f32_16x16x32_bf16 v[56:59], v[200:203], v[176:179], v[56:59]
	v_mfma_f32_16x16x32_bf16 v[60:63], v[208:211], v[176:179], v[60:63]
	ds_read_b128 v[164:167], v158 offset:24576
	ds_read_b128 v[168:171], v158 offset:26624
	ds_read_b128 v[172:175], v158 offset:28672
	ds_read_b128 v[176:179], v158 offset:30720
	s_waitcnt lgkmcnt(4)
	v_mfma_f32_16x16x32_bf16 v[64:67], v[200:203], v[136:139], v[64:67]
	v_mfma_f32_16x16x32_bf16 v[68:71], v[208:211], v[136:139], v[68:71]
	v_mfma_f32_16x16x32_bf16 v[72:75], v[200:203], v[140:143], v[72:75]
	v_mfma_f32_16x16x32_bf16 v[76:79], v[208:211], v[140:143], v[76:79]
	v_mfma_f32_16x16x32_bf16 v[80:83], v[200:203], v[144:147], v[80:83]
	v_mfma_f32_16x16x32_bf16 v[84:87], v[208:211], v[144:147], v[84:87]
	v_mfma_f32_16x16x32_bf16 v[88:91], v[200:203], v[148:151], v[88:91]
	v_mfma_f32_16x16x32_bf16 v[92:95], v[208:211], v[148:151], v[92:95]
	ds_read_b128 v[136:139], v159 offset:0
	ds_read_b128 v[140:143], v159 offset:2048
	ds_read_b128 v[144:147], v159 offset:4096
	s_waitcnt lgkmcnt(3)
	v_mfma_f32_16x16x32_bf16 v[96:99], v[200:203], v[164:167], v[96:99]
	v_mfma_f32_16x16x32_bf16 v[100:103], v[208:211], v[164:167], v[100:103]
	v_mfma_f32_16x16x32_bf16 v[104:107], v[200:203], v[168:171], v[104:107]
	v_mfma_f32_16x16x32_bf16 v[108:111], v[208:211], v[168:171], v[108:111]
	v_mfma_f32_16x16x32_bf16 v[112:115], v[200:203], v[172:175], v[112:115]
	v_mfma_f32_16x16x32_bf16 v[116:119], v[208:211], v[172:175], v[116:119]
	v_mfma_f32_16x16x32_bf16 v[120:123], v[200:203], v[176:179], v[120:123]
	v_mfma_f32_16x16x32_bf16 v[124:127], v[208:211], v[176:179], v[124:127]
	ds_read_b128 v[164:167], v159 offset:6144
	ds_read_b128 v[168:171], v159 offset:8192
	ds_read_b128 v[172:175], v159 offset:10240
	s_waitcnt lgkmcnt(3)
	v_mfma_f32_16x16x32_bf16 v[0:3], v[204:207], v[136:139], v[0:3]
	v_mfma_f32_16x16x32_bf16 v[4:7], v[240:243], v[136:139], v[4:7]
	v_mfma_f32_16x16x32_bf16 v[8:11], v[204:207], v[140:143], v[8:11]
	v_mfma_f32_16x16x32_bf16 v[12:15], v[240:243], v[140:143], v[12:15]
	v_mfma_f32_16x16x32_bf16 v[16:19], v[204:207], v[144:147], v[16:19]
	v_mfma_f32_16x16x32_bf16 v[20:23], v[240:243], v[144:147], v[20:23]
	ds_read_b128 v[136:139], v159 offset:12288
	ds_read_b128 v[140:143], v159 offset:14336
	ds_read_b128 v[144:147], v159 offset:16384
	ds_read_b128 v[148:151], v159 offset:18432
	ds_read_b128 v[152:155], v159 offset:20480
	s_waitcnt lgkmcnt(5)
	v_mfma_f32_16x16x32_bf16 v[24:27], v[204:207], v[164:167], v[24:27]
	v_mfma_f32_16x16x32_bf16 v[28:31], v[240:243], v[164:167], v[28:31]
	v_mfma_f32_16x16x32_bf16 v[32:35], v[204:207], v[168:171], v[32:35]
	v_mfma_f32_16x16x32_bf16 v[36:39], v[240:243], v[168:171], v[36:39]
	v_mfma_f32_16x16x32_bf16 v[40:43], v[204:207], v[172:175], v[40:43]
	v_mfma_f32_16x16x32_bf16 v[44:47], v[240:243], v[172:175], v[44:47]
	ds_read_b128 v[164:167], v159 offset:22528
	ds_read_b128 v[168:171], v159 offset:24576
	ds_read_b128 v[172:175], v159 offset:26624
	ds_read_b128 v[176:179], v159 offset:28672
	ds_read_b128 v[180:183], v159 offset:30720
	s_waitcnt lgkmcnt(5)
	v_mfma_f32_16x16x32_bf16 v[48:51], v[204:207], v[136:139], v[48:51]
	v_mfma_f32_16x16x32_bf16 v[52:55], v[240:243], v[136:139], v[52:55]
	v_mfma_f32_16x16x32_bf16 v[56:59], v[204:207], v[140:143], v[56:59]
	v_mfma_f32_16x16x32_bf16 v[60:63], v[240:243], v[140:143], v[60:63]
	v_mfma_f32_16x16x32_bf16 v[64:67], v[204:207], v[144:147], v[64:67]
	v_mfma_f32_16x16x32_bf16 v[68:71], v[240:243], v[144:147], v[68:71]
	v_mfma_f32_16x16x32_bf16 v[72:75], v[204:207], v[148:151], v[72:75]
	v_mfma_f32_16x16x32_bf16 v[76:79], v[240:243], v[148:151], v[76:79]
	v_mfma_f32_16x16x32_bf16 v[80:83], v[204:207], v[152:155], v[80:83]
	v_mfma_f32_16x16x32_bf16 v[84:87], v[240:243], v[152:155], v[84:87]
	s_waitcnt vmcnt(0) lgkmcnt(0)
	s_barrier
	s_cmp_ge_u32 s63, 62
	s_cbranch_scc1 .Lg2_ff2_nd16_1
	s_add_u32 s56, s56, 0x80
	s_addc_u32 s57, s57, 0
	s_add_u32 m0, s62, 0x8800
	s_add_u32 s4, s56, 0x0
	s_addc_u32 s5, s57, 0
	global_load_lds_dwordx4 v162, s[4:5]
	s_add_u32 m0, s62, 0x9800
	s_add_u32 s4, s56, 0x40000
	s_addc_u32 s5, s57, 0
	global_load_lds_dwordx4 v162, s[4:5]
	s_add_u32 m0, s62, 0xa800
	s_add_u32 s4, s56, 0x80000
	s_addc_u32 s5, s57, 0
	global_load_lds_dwordx4 v162, s[4:5]
	s_add_u32 m0, s62, 0xb800
	s_add_u32 s4, s56, 0xc0000
	s_addc_u32 s5, s57, 0
	global_load_lds_dwordx4 v162, s[4:5]
	s_add_u32 m0, s62, 0xc800
	s_add_u32 s4, s56, 0x100000
	s_addc_u32 s5, s57, 0
	global_load_lds_dwordx4 v162, s[4:5]
	s_add_u32 m0, s62, 0xd800
	s_add_u32 s4, s56, 0x140000
	s_addc_u32 s5, s57, 0
	global_load_lds_dwordx4 v162, s[4:5]
	s_add_u32 m0, s62, 0xe800
	s_add_u32 s4, s56, 0x180000
	s_addc_u32 s5, s57, 0
	global_load_lds_dwordx4 v162, s[4:5]
	s_add_u32 m0, s62, 0xf800
	s_add_u32 s4, s56, 0x1c0000
	s_addc_u32 s5, s57, 0
	global_load_lds_dwordx4 v162, s[4:5]
	ds_read_b128 v[136:139], v156 offset:0
	ds_read_b128 v[140:143], v156 offset:2048
	ds_read_b128 v[144:147], v156 offset:4096
	ds_read_b128 v[148:151], v156 offset:6144
.Lg2_ff2_nd16_1:
	v_mfma_f32_16x16x32_bf16 v[88:91], v[204:207], v[164:167], v[88:91]
	v_mfma_f32_16x16x32_bf16 v[92:95], v[240:243], v[164:167], v[92:95]
	v_mfma_f32_16x16x32_bf16 v[96:99], v[204:207], v[168:171], v[96:99]
	v_mfma_f32_16x16x32_bf16 v[100:103], v[240:243], v[168:171], v[100:103]
	v_mfma_f32_16x16x32_bf16 v[104:107], v[204:207], v[172:175], v[104:107]
	v_mfma_f32_16x16x32_bf16 v[108:111], v[240:243], v[172:175], v[108:111]
	v_mfma_f32_16x16x32_bf16 v[112:115], v[204:207], v[176:179], v[112:115]
	v_mfma_f32_16x16x32_bf16 v[116:119], v[240:243], v[176:179], v[116:119]
	v_mfma_f32_16x16x32_bf16 v[120:123], v[204:207], v[180:183], v[120:123]
	v_mfma_f32_16x16x32_bf16 v[124:127], v[240:243], v[180:183], v[124:127]
	s_add_i32 s63, s63, 2
	s_cmp_lt_u32 s63, 64
	s_cbranch_scc1 .Lg2_ff2_loop16
	s_branch .Lg2_ff2_episel

.Lg2_ff1_loop17:
	s_add_u32 s58, s58, 0x800
	s_addc_u32 s59, s59, 0
	global_load_dwordx4 v[200:203], v160, s[58:59] offset:0
	global_load_dwordx4 v[204:207], v160, s[58:59] offset:1024
	global_load_dwordx4 v[208:211], v161, s[58:59] offset:0
	global_load_dwordx4 v[240:243], v161, s[58:59] offset:1024
	ds_read_b128 v[164:167], v156 offset:8192
	ds_read_b128 v[168:171], v156 offset:10240
	ds_read_b128 v[172:175], v156 offset:12288
	ds_read_b128 v[176:179], v156 offset:14336
	s_waitcnt lgkmcnt(4)
	v_mfma_f32_16x16x32_bf16 v[0:3], v[184:187], v[136:139], v[0:3]
	v_mfma_f32_16x16x32_bf16 v[4:7], v[192:195], v[136:139], v[4:7]
	v_mfma_f32_16x16x32_bf16 v[8:11], v[184:187], v[140:143], v[8:11]
	v_mfma_f32_16x16x32_bf16 v[12:15], v[192:195], v[140:143], v[12:15]
	v_mfma_f32_16x16x32_bf16 v[16:19], v[184:187], v[144:147], v[16:19]
	v_mfma_f32_16x16x32_bf16 v[20:23], v[192:195], v[144:147], v[20:23]
	v_mfma_f32_16x16x32_bf16 v[24:27], v[184:187], v[148:151], v[24:27]
	v_mfma_f32_16x16x32_bf16 v[28:31], v[192:195], v[148:151], v[28:31]
	ds_read_b128 v[136:139], v156 offset:16384
	ds_read_b128 v[140:143], v156 offset:18432
	ds_read_b128 v[144:147], v156 offset:20480
	ds_read_b128 v[148:151], v156 offset:22528
	s_waitcnt lgkmcnt(4)
	v_mfma_f32_16x16x32_bf16 v[32:35], v[184:187], v[164:167], v[32:35]
	v_mfma_f32_16x16x32_bf16 v[36:39], v[192:195], v[164:167], v[36:39]
	v_mfma_f32_16x16x32_bf16 v[40:43], v[184:187], v[168:171], v[40:43]
	v_mfma_f32_16x16x32_bf16 v[44:47], v[192:195], v[168:171], v[44:47]
	v_mfma_f32_16x16x32_bf16 v[48:51], v[184:187], v[172:175], v[48:51]
	v_mfma_f32_16x16x32_bf16 v[52:55], v[192:195], v[172:175], v[52:55]
	v_mfma_f32_16x16x32_bf16 v[56:59], v[184:187], v[176:179], v[56:59]
	v_mfma_f32_16x16x32_bf16 v[60:63], v[192:195], v[176:179], v[60:63]
	ds_read_b128 v[164:167], v156 offset:24576
	ds_read_b128 v[168:171], v156 offset:26624
	ds_read_b128 v[172:175], v156 offset:28672
	ds_read_b128 v[176:179], v156 offset:30720
	ds_read_b128 v[180:183], v156 offset:32768
	s_waitcnt lgkmcnt(5)
	v_mfma_f32_16x16x32_bf16 v[64:67], v[184:187], v[136:139], v[64:67]
	v_mfma_f32_16x16x32_bf16 v[68:71], v[192:195], v[136:139], v[68:71]
	v_mfma_f32_16x16x32_bf16 v[72:75], v[184:187], v[140:143], v[72:75]
	v_mfma_f32_16x16x32_bf16 v[76:79], v[192:195], v[140:143], v[76:79]
	v_mfma_f32_16x16x32_bf16 v[80:83], v[184:187], v[144:147], v[80:83]
	v_mfma_f32_16x16x32_bf16 v[84:87], v[192:195], v[144:147], v[84:87]
	v_mfma_f32_16x16x32_bf16 v[88:91], v[184:187], v[148:151], v[88:91]
	v_mfma_f32_16x16x32_bf16 v[92:95], v[192:195], v[148:151], v[92:95]
	ds_read_b128 v[136:139], v157 offset:0
	ds_read_b128 v[140:143], v157 offset:2048
	ds_read_b128 v[144:147], v157 offset:4096
	s_waitcnt lgkmcnt(3)
	v_mfma_f32_16x16x32_bf16 v[96:99], v[184:187], v[164:167], v[96:99]
	v_mfma_f32_16x16x32_bf16 v[100:103], v[192:195], v[164:167], v[100:103]
	v_mfma_f32_16x16x32_bf16 v[104:107], v[184:187], v[168:171], v[104:107]
	v_mfma_f32_16x16x32_bf16 v[108:111], v[192:195], v[168:171], v[108:111]
	v_mfma_f32_16x16x32_bf16 v[112:115], v[184:187], v[172:175], v[112:115]
	v_mfma_f32_16x16x32_bf16 v[116:119], v[192:195], v[172:175], v[116:119]
	v_mfma_f32_16x16x32_bf16 v[120:123], v[184:187], v[176:179], v[120:123]
	v_mfma_f32_16x16x32_bf16 v[124:127], v[192:195], v[176:179], v[124:127]
	v_mfma_f32_16x16x32_bf16 v[128:131], v[184:187], v[180:183], v[128:131]
	v_mfma_f32_16x16x32_bf16 v[132:135], v[192:195], v[180:183], v[132:135]
	ds_read_b128 v[164:167], v157 offset:6144
	ds_read_b128 v[168:171], v157 offset:8192
	ds_read_b128 v[172:175], v157 offset:10240
	ds_read_b128 v[176:179], v157 offset:12288
	s_waitcnt lgkmcnt(4)
	v_mfma_f32_16x16x32_bf16 v[0:3], v[188:191], v[136:139], v[0:3]
	v_mfma_f32_16x16x32_bf16 v[4:7], v[196:199], v[136:139], v[4:7]
	v_mfma_f32_16x16x32_bf16 v[8:11], v[188:191], v[140:143], v[8:11]
	v_mfma_f32_16x16x32_bf16 v[12:15], v[196:199], v[140:143], v[12:15]
	v_mfma_f32_16x16x32_bf16 v[16:19], v[188:191], v[144:147], v[16:19]
	v_mfma_f32_16x16x32_bf16 v[20:23], v[196:199], v[144:147], v[20:23]
	ds_read_b128 v[136:139], v157 offset:14336
	ds_read_b128 v[140:143], v157 offset:16384
	ds_read_b128 v[144:147], v157 offset:18432
	ds_read_b128 v[148:151], v157 offset:20480
	ds_read_b128 v[152:155], v157 offset:22528
	s_waitcnt lgkmcnt(5)
	v_mfma_f32_16x16x32_bf16 v[24:27], v[188:191], v[164:167], v[24:27]
	v_mfma_f32_16x16x32_bf16 v[28:31], v[196:199], v[164:167], v[28:31]
	v_mfma_f32_16x16x32_bf16 v[32:35], v[188:191], v[168:171], v[32:35]
	v_mfma_f32_16x16x32_bf16 v[36:39], v[196:199], v[168:171], v[36:39]
	v_mfma_f32_16x16x32_bf16 v[40:43], v[188:191], v[172:175], v[40:43]
	v_mfma_f32_16x16x32_bf16 v[44:47], v[196:199], v[172:175], v[44:47]
	v_mfma_f32_16x16x32_bf16 v[48:51], v[188:191], v[176:179], v[48:51]
	v_mfma_f32_16x16x32_bf16 v[52:55], v[196:199], v[176:179], v[52:55]
	ds_read_b128 v[164:167], v157 offset:24576
	ds_read_b128 v[168:171], v157 offset:26624
	ds_read_b128 v[172:175], v157 offset:28672
	ds_read_b128 v[176:179], v157 offset:30720
	ds_read_b128 v[180:183], v157 offset:32768
	s_waitcnt lgkmcnt(5)
	v_mfma_f32_16x16x32_bf16 v[56:59], v[188:191], v[136:139], v[56:59]
	v_mfma_f32_16x16x32_bf16 v[60:63], v[196:199], v[136:139], v[60:63]
	v_mfma_f32_16x16x32_bf16 v[64:67], v[188:191], v[140:143], v[64:67]
	v_mfma_f32_16x16x32_bf16 v[68:71], v[196:199], v[140:143], v[68:71]
	v_mfma_f32_16x16x32_bf16 v[72:75], v[188:191], v[144:147], v[72:75]
	v_mfma_f32_16x16x32_bf16 v[76:79], v[196:199], v[144:147], v[76:79]
	v_mfma_f32_16x16x32_bf16 v[80:83], v[188:191], v[148:151], v[80:83]
	v_mfma_f32_16x16x32_bf16 v[84:87], v[196:199], v[148:151], v[84:87]
	v_mfma_f32_16x16x32_bf16 v[88:91], v[188:191], v[152:155], v[88:91]
	v_mfma_f32_16x16x32_bf16 v[92:95], v[196:199], v[152:155], v[92:95]
	s_waitcnt vmcnt(0) lgkmcnt(0)
	s_barrier
	s_cmp_ge_u32 s63, 14
	s_cbranch_scc1 .Lg2_ff1_nd17_0
	s_add_u32 s56, s56, 0x80
	s_addc_u32 s57, s57, 0
	s_add_u32 m0, s62, 0x0
	s_add_u32 s4, s56, 0x0
	s_addc_u32 s5, s57, 0
	global_load_lds_dwordx4 v162, s[4:5]
	s_add_u32 m0, s62, 0x1000
	s_add_u32 s4, s56, 0x10000
	s_addc_u32 s5, s57, 0
	global_load_lds_dwordx4 v162, s[4:5]
	s_add_u32 m0, s62, 0x2000
	s_add_u32 s4, s56, 0x20000
	s_addc_u32 s5, s57, 0
	global_load_lds_dwordx4 v162, s[4:5]
	s_add_u32 m0, s62, 0x3000
	s_add_u32 s4, s56, 0x30000
	s_addc_u32 s5, s57, 0
	global_load_lds_dwordx4 v162, s[4:5]
	s_add_u32 m0, s62, 0x4000
	s_add_u32 s4, s56, 0x40000
	s_addc_u32 s5, s57, 0
	global_load_lds_dwordx4 v162, s[4:5]
	s_add_u32 m0, s62, 0x5000
	s_add_u32 s4, s56, 0x50000
	s_addc_u32 s5, s57, 0
	global_load_lds_dwordx4 v162, s[4:5]
	s_add_u32 m0, s62, 0x6000
	s_add_u32 s4, s56, 0x60000
	s_addc_u32 s5, s57, 0
	global_load_lds_dwordx4 v162, s[4:5]
	s_add_u32 m0, s62, 0x7000
	s_add_u32 s4, s56, 0x70000
	s_addc_u32 s5, s57, 0
	global_load_lds_dwordx4 v162, s[4:5]
	s_cmp_gt_u32 s70, 1
	s_cbranch_scc1 .Lg2_ff1_nodma_2
	s_add_u32 m0, s62, 0x8000
	s_add_u32 s4, s56, 0x80000
	s_addc_u32 s5, s57, 0
	global_load_lds_dwordx4 v162, s[4:5]

.Lg2_ff1_nb17_1:
	ds_read_b128 v[164:167], v158 offset:8192
	ds_read_b128 v[168:171], v158 offset:10240
	ds_read_b128 v[172:175], v158 offset:12288
	ds_read_b128 v[176:179], v158 offset:14336
	s_waitcnt lgkmcnt(4)
	v_mfma_f32_16x16x32_bf16 v[0:3], v[200:203], v[136:139], v[0:3]
	v_mfma_f32_16x16x32_bf16 v[4:7], v[208:211], v[136:139], v[4:7]
	v_mfma_f32_16x16x32_bf16 v[8:11], v[200:203], v[140:143], v[8:11]
	v_mfma_f32_16x16x32_bf16 v[12:15], v[208:211], v[140:143], v[12:15]
	v_mfma_f32_16x16x32_bf16 v[16:19], v[200:203], v[144:147], v[16:19]
	v_mfma_f32_16x16x32_bf16 v[20:23], v[208:211], v[144:147], v[20:23]
	v_mfma_f32_16x16x32_bf16 v[24:27], v[200:203], v[148:151], v[24:27]
	v_mfma_f32_16x16x32_bf16 v[28:31], v[208:211], v[148:151], v[28:31]
	ds_read_b128 v[136:139], v158 offset:16384
	ds_read_b128 v[140:143], v158 offset:18432
	ds_read_b128 v[144:147], v158 offset:20480
	ds_read_b128 v[148:151], v158 offset:22528
	s_waitcnt lgkmcnt(4)
	v_mfma_f32_16x16x32_bf16 v[32:35], v[200:203], v[164:167], v[32:35]
	v_mfma_f32_16x16x32_bf16 v[36:39], v[208:211], v[164:167], v[36:39]
	v_mfma_f32_16x16x32_bf16 v[40:43], v[200:203], v[168:171], v[40:43]
	v_mfma_f32_16x16x32_bf16 v[44:47], v[208:211], v[168:171], v[44:47]
	v_mfma_f32_16x16x32_bf16 v[48:51], v[200:203], v[172:175], v[48:51]
	v_mfma_f32_16x16x32_bf16 v[52:55], v[208:211], v[172:175], v[52:55]
	v_mfma_f32_16x16x32_bf16 v[56:59], v[200:203], v[176:179], v[56:59]
	v_mfma_f32_16x16x32_bf16 v[60:63], v[208:211], v[176:179], v[60:63]
	ds_read_b128 v[164:167], v158 offset:24576
	ds_read_b128 v[168:171], v158 offset:26624
	ds_read_b128 v[172:175], v158 offset:28672
	ds_read_b128 v[176:179], v158 offset:30720
	ds_read_b128 v[180:183], v158 offset:32768
	s_waitcnt lgkmcnt(5)
	v_mfma_f32_16x16x32_bf16 v[64:67], v[200:203], v[136:139], v[64:67]
	v_mfma_f32_16x16x32_bf16 v[68:71], v[208:211], v[136:139], v[68:71]
	v_mfma_f32_16x16x32_bf16 v[72:75], v[200:203], v[140:143], v[72:75]
	v_mfma_f32_16x16x32_bf16 v[76:79], v[208:211], v[140:143], v[76:79]
	v_mfma_f32_16x16x32_bf16 v[80:83], v[200:203], v[144:147], v[80:83]
	v_mfma_f32_16x16x32_bf16 v[84:87], v[208:211], v[144:147], v[84:87]
	v_mfma_f32_16x16x32_bf16 v[88:91], v[200:203], v[148:151], v[88:91]
	v_mfma_f32_16x16x32_bf16 v[92:95], v[208:211], v[148:151], v[92:95]
	ds_read_b128 v[136:139], v159 offset:0
	ds_read_b128 v[140:143], v159 offset:2048
	ds_read_b128 v[144:147], v159 offset:4096
	s_waitcnt lgkmcnt(3)
	v_mfma_f32_16x16x32_bf16 v[96:99], v[200:203], v[164:167], v[96:99]
	v_mfma_f32_16x16x32_bf16 v[100:103], v[208:211], v[164:167], v[100:103]
	v_mfma_f32_16x16x32_bf16 v[104:107], v[200:203], v[168:171], v[104:107]
	v_mfma_f32_16x16x32_bf16 v[108:111], v[208:211], v[168:171], v[108:111]
	v_mfma_f32_16x16x32_bf16 v[112:115], v[200:203], v[172:175], v[112:115]
	v_mfma_f32_16x16x32_bf16 v[116:119], v[208:211], v[172:175], v[116:119]
	v_mfma_f32_16x16x32_bf16 v[120:123], v[200:203], v[176:179], v[120:123]
	v_mfma_f32_16x16x32_bf16 v[124:127], v[208:211], v[176:179], v[124:127]
	v_mfma_f32_16x16x32_bf16 v[128:131], v[200:203], v[180:183], v[128:131]
	v_mfma_f32_16x16x32_bf16 v[132:135], v[208:211], v[180:183], v[132:135]
	ds_read_b128 v[164:167], v159 offset:6144
	ds_read_b128 v[168:171], v159 offset:8192
	ds_read_b128 v[172:175], v159 offset:10240
	ds_read_b128 v[176:179], v159 offset:12288
	s_waitcnt lgkmcnt(4)
	v_mfma_f32_16x16x32_bf16 v[0:3], v[204:207], v[136:139], v[0:3]
	v_mfma_f32_16x16x32_bf16 v[4:7], v[240:243], v[136:139], v[4:7]
	v_mfma_f32_16x16x32_bf16 v[8:11], v[204:207], v[140:143], v[8:11]
	v_mfma_f32_16x16x32_bf16 v[12:15], v[240:243], v[140:143], v[12:15]
	v_mfma_f32_16x16x32_bf16 v[16:19], v[204:207], v[144:147], v[16:19]
	v_mfma_f32_16x16x32_bf16 v[20:23], v[240:243], v[144:147], v[20:23]
	ds_read_b128 v[136:139], v159 offset:14336
	ds_read_b128 v[140:143], v159 offset:16384
	ds_read_b128 v[144:147], v159 offset:18432
	ds_read_b128 v[148:151], v159 offset:20480
	ds_read_b128 v[152:155], v159 offset:22528
	s_waitcnt lgkmcnt(5)
	v_mfma_f32_16x16x32_bf16 v[24:27], v[204:207], v[164:167], v[24:27]
	v_mfma_f32_16x16x32_bf16 v[28:31], v[240:243], v[164:167], v[28:31]
	v_mfma_f32_16x16x32_bf16 v[32:35], v[204:207], v[168:171], v[32:35]
	v_mfma_f32_16x16x32_bf16 v[36:39], v[240:243], v[168:171], v[36:39]
	v_mfma_f32_16x16x32_bf16 v[40:43], v[204:207], v[172:175], v[40:43]
	v_mfma_f32_16x16x32_bf16 v[44:47], v[240:243], v[172:175], v[44:47]
	v_mfma_f32_16x16x32_bf16 v[48:51], v[204:207], v[176:179], v[48:51]
	v_mfma_f32_16x16x32_bf16 v[52:55], v[240:243], v[176:179], v[52:55]
	ds_read_b128 v[164:167], v159 offset:24576
	ds_read_b128 v[168:171], v159 offset:26624
	ds_read_b128 v[172:175], v159 offset:28672
	ds_read_b128 v[176:179], v159 offset:30720
	ds_read_b128 v[180:183], v159 offset:32768
	s_waitcnt lgkmcnt(5)
	v_mfma_f32_16x16x32_bf16 v[56:59], v[204:207], v[136:139], v[56:59]
	v_mfma_f32_16x16x32_bf16 v[60:63], v[240:243], v[136:139], v[60:63]
	v_mfma_f32_16x16x32_bf16 v[64:67], v[204:207], v[140:143], v[64:67]
	v_mfma_f32_16x16x32_bf16 v[68:71], v[240:243], v[140:143], v[68:71]
	v_mfma_f32_16x16x32_bf16 v[72:75], v[204:207], v[144:147], v[72:75]
	v_mfma_f32_16x16x32_bf16 v[76:79], v[240:243], v[144:147], v[76:79]
	v_mfma_f32_16x16x32_bf16 v[80:83], v[204:207], v[148:151], v[80:83]
	v_mfma_f32_16x16x32_bf16 v[84:87], v[240:243], v[148:151], v[84:87]
	v_mfma_f32_16x16x32_bf16 v[88:91], v[204:207], v[152:155], v[88:91]
	v_mfma_f32_16x16x32_bf16 v[92:95], v[240:243], v[152:155], v[92:95]
	s_waitcnt vmcnt(0) lgkmcnt(0)
	s_barrier
	s_cmp_ge_u32 s63, 14
	s_cbranch_scc1 .Lg2_ff1_nd17_1
	s_add_u32 s56, s56, 0x80
	s_addc_u32 s57, s57, 0
	s_add_u32 m0, s62, 0x8800
	s_add_u32 s4, s56, 0x0
	s_addc_u32 s5, s57, 0
	global_load_lds_dwordx4 v162, s[4:5]
	s_add_u32 m0, s62, 0x9800
	s_add_u32 s4, s56, 0x10000
	s_addc_u32 s5, s57, 0
	global_load_lds_dwordx4 v162, s[4:5]
	s_add_u32 m0, s62, 0xa800
	s_add_u32 s4, s56, 0x20000
	s_addc_u32 s5, s57, 0
	global_load_lds_dwordx4 v162, s[4:5]
	s_add_u32 m0, s62, 0xb800
	s_add_u32 s4, s56, 0x30000
	s_addc_u32 s5, s57, 0
	global_load_lds_dwordx4 v162, s[4:5]
	s_add_u32 m0, s62, 0xc800
	s_add_u32 s4, s56, 0x40000
	s_addc_u32 s5, s57, 0
	global_load_lds_dwordx4 v162, s[4:5]
	s_add_u32 m0, s62, 0xd800
	s_add_u32 s4, s56, 0x50000
	s_addc_u32 s5, s57, 0
	global_load_lds_dwordx4 v162, s[4:5]
	s_add_u32 m0, s62, 0xe800
	s_add_u32 s4, s56, 0x60000
	s_addc_u32 s5, s57, 0
	global_load_lds_dwordx4 v162, s[4:5]
	s_add_u32 m0, s62, 0xf800
	s_add_u32 s4, s56, 0x70000
	s_addc_u32 s5, s57, 0
	global_load_lds_dwordx4 v162, s[4:5]
	s_cmp_gt_u32 s70, 1
	s_cbranch_scc1 .Lg2_ff1_nodma_3
	s_add_u32 m0, s62, 0x10800
	s_add_u32 s4, s56, 0x80000
	s_addc_u32 s5, s57, 0
	global_load_lds_dwordx4 v162, s[4:5]

.Lg2_ff1_loop16:
	s_add_u32 s58, s58, 0x800
	s_addc_u32 s59, s59, 0
	global_load_dwordx4 v[200:203], v160, s[58:59] offset:0
	global_load_dwordx4 v[204:207], v160, s[58:59] offset:1024
	global_load_dwordx4 v[208:211], v161, s[58:59] offset:0
	global_load_dwordx4 v[240:243], v161, s[58:59] offset:1024
	ds_read_b128 v[164:167], v156 offset:8192
	ds_read_b128 v[168:171], v156 offset:10240
	ds_read_b128 v[172:175], v156 offset:12288
	ds_read_b128 v[176:179], v156 offset:14336
	s_waitcnt lgkmcnt(4)
	v_mfma_f32_16x16x32_bf16 v[0:3], v[184:187], v[136:139], v[0:3]
	v_mfma_f32_16x16x32_bf16 v[4:7], v[192:195], v[136:139], v[4:7]
	v_mfma_f32_16x16x32_bf16 v[8:11], v[184:187], v[140:143], v[8:11]
	v_mfma_f32_16x16x32_bf16 v[12:15], v[192:195], v[140:143], v[12:15]
	v_mfma_f32_16x16x32_bf16 v[16:19], v[184:187], v[144:147], v[16:19]
	v_mfma_f32_16x16x32_bf16 v[20:23], v[192:195], v[144:147], v[20:23]
	v_mfma_f32_16x16x32_bf16 v[24:27], v[184:187], v[148:151], v[24:27]
	v_mfma_f32_16x16x32_bf16 v[28:31], v[192:195], v[148:151], v[28:31]
	ds_read_b128 v[136:139], v156 offset:16384
	ds_read_b128 v[140:143], v156 offset:18432
	ds_read_b128 v[144:147], v156 offset:20480
	ds_read_b128 v[148:151], v156 offset:22528
	s_waitcnt lgkmcnt(4)
	v_mfma_f32_16x16x32_bf16 v[32:35], v[184:187], v[164:167], v[32:35]
	v_mfma_f32_16x16x32_bf16 v[36:39], v[192:195], v[164:167], v[36:39]
	v_mfma_f32_16x16x32_bf16 v[40:43], v[184:187], v[168:171], v[40:43]
	v_mfma_f32_16x16x32_bf16 v[44:47], v[192:195], v[168:171], v[44:47]
	v_mfma_f32_16x16x32_bf16 v[48:51], v[184:187], v[172:175], v[48:51]
	v_mfma_f32_16x16x32_bf16 v[52:55], v[192:195], v[172:175], v[52:55]
	v_mfma_f32_16x16x32_bf16 v[56:59], v[184:187], v[176:179], v[56:59]
	v_mfma_f32_16x16x32_bf16 v[60:63], v[192:195], v[176:179], v[60:63]
	ds_read_b128 v[164:167], v156 offset:24576
	ds_read_b128 v[168:171], v156 offset:26624
	ds_read_b128 v[172:175], v156 offset:28672
	ds_read_b128 v[176:179], v156 offset:30720
	s_waitcnt lgkmcnt(4)
	v_mfma_f32_16x16x32_bf16 v[64:67], v[184:187], v[136:139], v[64:67]
	v_mfma_f32_16x16x32_bf16 v[68:71], v[192:195], v[136:139], v[68:71]
	v_mfma_f32_16x16x32_bf16 v[72:75], v[184:187], v[140:143], v[72:75]
	v_mfma_f32_16x16x32_bf16 v[76:79], v[192:195], v[140:143], v[76:79]
	v_mfma_f32_16x16x32_bf16 v[80:83], v[184:187], v[144:147], v[80:83]
	v_mfma_f32_16x16x32_bf16 v[84:87], v[192:195], v[144:147], v[84:87]
	v_mfma_f32_16x16x32_bf16 v[88:91], v[184:187], v[148:151], v[88:91]
	v_mfma_f32_16x16x32_bf16 v[92:95], v[192:195], v[148:151], v[92:95]
	ds_read_b128 v[136:139], v157 offset:0
	ds_read_b128 v[140:143], v157 offset:2048
	ds_read_b128 v[144:147], v157 offset:4096
	s_waitcnt lgkmcnt(3)
	v_mfma_f32_16x16x32_bf16 v[96:99], v[184:187], v[164:167], v[96:99]
	v_mfma_f32_16x16x32_bf16 v[100:103], v[192:195], v[164:167], v[100:103]
	v_mfma_f32_16x16x32_bf16 v[104:107], v[184:187], v[168:171], v[104:107]
	v_mfma_f32_16x16x32_bf16 v[108:111], v[192:195], v[168:171], v[108:111]
	v_mfma_f32_16x16x32_bf16 v[112:115], v[184:187], v[172:175], v[112:115]
	v_mfma_f32_16x16x32_bf16 v[116:119], v[192:195], v[172:175], v[116:119]
	v_mfma_f32_16x16x32_bf16 v[120:123], v[184:187], v[176:179], v[120:123]
	v_mfma_f32_16x16x32_bf16 v[124:127], v[192:195], v[176:179], v[124:127]
	ds_read_b128 v[164:167], v157 offset:6144
	ds_read_b128 v[168:171], v157 offset:8192
	ds_read_b128 v[172:175], v157 offset:10240
	s_waitcnt lgkmcnt(3)
	v_mfma_f32_16x16x32_bf16 v[0:3], v[188:191], v[136:139], v[0:3]
	v_mfma_f32_16x16x32_bf16 v[4:7], v[196:199], v[136:139], v[4:7]
	v_mfma_f32_16x16x32_bf16 v[8:11], v[188:191], v[140:143], v[8:11]
	v_mfma_f32_16x16x32_bf16 v[12:15], v[196:199], v[140:143], v[12:15]
	v_mfma_f32_16x16x32_bf16 v[16:19], v[188:191], v[144:147], v[16:19]
	v_mfma_f32_16x16x32_bf16 v[20:23], v[196:199], v[144:147], v[20:23]
	ds_read_b128 v[136:139], v157 offset:12288
	ds_read_b128 v[140:143], v157 offset:14336
	ds_read_b128 v[144:147], v157 offset:16384
	ds_read_b128 v[148:151], v157 offset:18432
	ds_read_b128 v[152:155], v157 offset:20480
	s_waitcnt lgkmcnt(5)
	v_mfma_f32_16x16x32_bf16 v[24:27], v[188:191], v[164:167], v[24:27]
	v_mfma_f32_16x16x32_bf16 v[28:31], v[196:199], v[164:167], v[28:31]
	v_mfma_f32_16x16x32_bf16 v[32:35], v[188:191], v[168:171], v[32:35]
	v_mfma_f32_16x16x32_bf16 v[36:39], v[196:199], v[168:171], v[36:39]
	v_mfma_f32_16x16x32_bf16 v[40:43], v[188:191], v[172:175], v[40:43]
	v_mfma_f32_16x16x32_bf16 v[44:47], v[196:199], v[172:175], v[44:47]
	ds_read_b128 v[164:167], v157 offset:22528
	ds_read_b128 v[168:171], v157 offset:24576
	ds_read_b128 v[172:175], v157 offset:26624
	ds_read_b128 v[176:179], v157 offset:28672
	ds_read_b128 v[180:183], v157 offset:30720
	s_waitcnt lgkmcnt(5)
	v_mfma_f32_16x16x32_bf16 v[48:51], v[188:191], v[136:139], v[48:51]
	v_mfma_f32_16x16x32_bf16 v[52:55], v[196:199], v[136:139], v[52:55]
	v_mfma_f32_16x16x32_bf16 v[56:59], v[188:191], v[140:143], v[56:59]
	v_mfma_f32_16x16x32_bf16 v[60:63], v[196:199], v[140:143], v[60:63]
	v_mfma_f32_16x16x32_bf16 v[64:67], v[188:191], v[144:147], v[64:67]
	v_mfma_f32_16x16x32_bf16 v[68:71], v[196:199], v[144:147], v[68:71]
	v_mfma_f32_16x16x32_bf16 v[72:75], v[188:191], v[148:151], v[72:75]
	v_mfma_f32_16x16x32_bf16 v[76:79], v[196:199], v[148:151], v[76:79]
	v_mfma_f32_16x16x32_bf16 v[80:83], v[188:191], v[152:155], v[80:83]
	v_mfma_f32_16x16x32_bf16 v[84:87], v[196:199], v[152:155], v[84:87]
	s_waitcnt vmcnt(0) lgkmcnt(0)
	s_barrier
	s_cmp_ge_u32 s63, 14
	s_cbranch_scc1 .Lg2_ff1_nd16_0
	s_add_u32 s56, s56, 0x80
	s_addc_u32 s57, s57, 0
	s_add_u32 m0, s62, 0x0
	s_add_u32 s4, s56, 0x0
	s_addc_u32 s5, s57, 0
	global_load_lds_dwordx4 v162, s[4:5]
	s_add_u32 m0, s62, 0x1000
	s_add_u32 s4, s56, 0x10000
	s_addc_u32 s5, s57, 0
	global_load_lds_dwordx4 v162, s[4:5]
	s_add_u32 m0, s62, 0x2000
	s_add_u32 s4, s56, 0x20000
	s_addc_u32 s5, s57, 0
	global_load_lds_dwordx4 v162, s[4:5]
	s_add_u32 m0, s62, 0x3000
	s_add_u32 s4, s56, 0x30000
	s_addc_u32 s5, s57, 0
	global_load_lds_dwordx4 v162, s[4:5]
	s_add_u32 m0, s62, 0x4000
	s_add_u32 s4, s56, 0x40000
	s_addc_u32 s5, s57, 0
	global_load_lds_dwordx4 v162, s[4:5]
	s_add_u32 m0, s62, 0x5000
	s_add_u32 s4, s56, 0x50000
	s_addc_u32 s5, s57, 0
	global_load_lds_dwordx4 v162, s[4:5]
	s_add_u32 m0, s62, 0x6000
	s_add_u32 s4, s56, 0x60000
	s_addc_u32 s5, s57, 0
	global_load_lds_dwordx4 v162, s[4:5]
	s_add_u32 m0, s62, 0x7000
	s_add_u32 s4, s56, 0x70000
	s_addc_u32 s5, s57, 0
	global_load_lds_dwordx4 v162, s[4:5]
.Lg2_ff1_nd16_0:
	ds_read_b128 v[136:139], v158 offset:0
	ds_read_b128 v[140:143], v158 offset:2048
	ds_read_b128 v[144:147], v158 offset:4096
	ds_read_b128 v[148:151], v158 offset:6144
	v_mfma_f32_16x16x32_bf16 v[88:91], v[188:191], v[164:167], v[88:91]
	v_mfma_f32_16x16x32_bf16 v[92:95], v[196:199], v[164:167], v[92:95]
	v_mfma_f32_16x16x32_bf16 v[96:99], v[188:191], v[168:171], v[96:99]
	v_mfma_f32_16x16x32_bf16 v[100:103], v[196:199], v[168:171], v[100:103]
	v_mfma_f32_16x16x32_bf16 v[104:107], v[188:191], v[172:175], v[104:107]
	v_mfma_f32_16x16x32_bf16 v[108:111], v[196:199], v[172:175], v[108:111]
	v_mfma_f32_16x16x32_bf16 v[112:115], v[188:191], v[176:179], v[112:115]
	v_mfma_f32_16x16x32_bf16 v[116:119], v[196:199], v[176:179], v[116:119]
	v_mfma_f32_16x16x32_bf16 v[120:123], v[188:191], v[180:183], v[120:123]
	v_mfma_f32_16x16x32_bf16 v[124:127], v[196:199], v[180:183], v[124:127]
	s_cmp_ge_u32 s63, 14
	s_cbranch_scc1 .Lg2_ff1_nb16_1
	s_add_u32 s58, s58, 0x800
	s_addc_u32 s59, s59, 0
	global_load_dwordx4 v[184:187], v160, s[58:59] offset:0
	global_load_dwordx4 v[188:191], v160, s[58:59] offset:1024
	global_load_dwordx4 v[192:195], v161, s[58:59] offset:0
	global_load_dwordx4 v[196:199], v161, s[58:59] offset:1024
.Lg2_ff1_nb16_1:
	ds_read_b128 v[164:167], v158 offset:8192
	ds_read_b128 v[168:171], v158 offset:10240
	ds_read_b128 v[172:175], v158 offset:12288
	ds_read_b128 v[176:179], v158 offset:14336
	s_waitcnt lgkmcnt(4)
	v_mfma_f32_16x16x32_bf16 v[0:3], v[200:203], v[136:139], v[0:3]
	v_mfma_f32_16x16x32_bf16 v[4:7], v[208:211], v[136:139], v[4:7]
	v_mfma_f32_16x16x32_bf16 v[8:11], v[200:203], v[140:143], v[8:11]
	v_mfma_f32_16x16x32_bf16 v[12:15], v[208:211], v[140:143], v[12:15]
	v_mfma_f32_16x16x32_bf16 v[16:19], v[200:203], v[144:147], v[16:19]
	v_mfma_f32_16x16x32_bf16 v[20:23], v[208:211], v[144:147], v[20:23]
	v_mfma_f32_16x16x32_bf16 v[24:27], v[200:203], v[148:151], v[24:27]
	v_mfma_f32_16x16x32_bf16 v[28:31], v[208:211], v[148:151], v[28:31]
	ds_read_b128 v[136:139], v158 offset:16384
	ds_read_b128 v[140:143], v158 offset:18432
	ds_read_b128 v[144:147], v158 offset:20480
	ds_read_b128 v[148:151], v158 offset:22528
	s_waitcnt lgkmcnt(4)
	v_mfma_f32_16x16x32_bf16 v[32:35], v[200:203], v[164:167], v[32:35]
	v_mfma_f32_16x16x32_bf16 v[36:39], v[208:211], v[164:167], v[36:39]
	v_mfma_f32_16x16x32_bf16 v[40:43], v[200:203], v[168:171], v[40:43]
	v_mfma_f32_16x16x32_bf16 v[44:47], v[208:211], v[168:171], v[44:47]
	v_mfma_f32_16x16x32_bf16 v[48:51], v[200:203], v[172:175], v[48:51]
	v_mfma_f32_16x16x32_bf16 v[52:55], v[208:211], v[172:175], v[52:55]
	v_mfma_f32_16x16x32_bf16 v[56:59], v[200:203], v[176:179], v[56:59]
	v_mfma_f32_16x16x32_bf16 v[60:63], v[208:211], v[176:179], v[60:63]
	ds_read_b128 v[164:167], v158 offset:24576
	ds_read_b128 v[168:171], v158 offset:26624
	ds_read_b128 v[172:175], v158 offset:28672
	ds_read_b128 v[176:179], v158 offset:30720
	s_waitcnt lgkmcnt(4)
	v_mfma_f32_16x16x32_bf16 v[64:67], v[200:203], v[136:139], v[64:67]
	v_mfma_f32_16x16x32_bf16 v[68:71], v[208:211], v[136:139], v[68:71]
	v_mfma_f32_16x16x32_bf16 v[72:75], v[200:203], v[140:143], v[72:75]
	v_mfma_f32_16x16x32_bf16 v[76:79], v[208:211], v[140:143], v[76:79]
	v_mfma_f32_16x16x32_bf16 v[80:83], v[200:203], v[144:147], v[80:83]
	v_mfma_f32_16x16x32_bf16 v[84:87], v[208:211], v[144:147], v[84:87]
	v_mfma_f32_16x16x32_bf16 v[88:91], v[200:203], v[148:151], v[88:91]
	v_mfma_f32_16x16x32_bf16 v[92:95], v[208:211], v[148:151], v[92:95]
	ds_read_b128 v[136:139], v159 offset:0
	ds_read_b128 v[140:143], v159 offset:2048
	ds_read_b128 v[144:147], v159 offset:4096
	s_waitcnt lgkmcnt(3)
	v_mfma_f32_16x16x32_bf16 v[96:99], v[200:203], v[164:167], v[96:99]
	v_mfma_f32_16x16x32_bf16 v[100:103], v[208:211], v[164:167], v[100:103]
	v_mfma_f32_16x16x32_bf16 v[104:107], v[200:203], v[168:171], v[104:107]
	v_mfma_f32_16x16x32_bf16 v[108:111], v[208:211], v[168:171], v[108:111]
	v_mfma_f32_16x16x32_bf16 v[112:115], v[200:203], v[172:175], v[112:115]
	v_mfma_f32_16x16x32_bf16 v[116:119], v[208:211], v[172:175], v[116:119]
	v_mfma_f32_16x16x32_bf16 v[120:123], v[200:203], v[176:179], v[120:123]
	v_mfma_f32_16x16x32_bf16 v[124:127], v[208:211], v[176:179], v[124:127]
	ds_read_b128 v[164:167], v159 offset:6144
	ds_read_b128 v[168:171], v159 offset:8192
	ds_read_b128 v[172:175], v159 offset:10240
	s_waitcnt lgkmcnt(3)
	v_mfma_f32_16x16x32_bf16 v[0:3], v[204:207], v[136:139], v[0:3]
	v_mfma_f32_16x16x32_bf16 v[4:7], v[240:243], v[136:139], v[4:7]
	v_mfma_f32_16x16x32_bf16 v[8:11], v[204:207], v[140:143], v[8:11]
	v_mfma_f32_16x16x32_bf16 v[12:15], v[240:243], v[140:143], v[12:15]
	v_mfma_f32_16x16x32_bf16 v[16:19], v[204:207], v[144:147], v[16:19]
	v_mfma_f32_16x16x32_bf16 v[20:23], v[240:243], v[144:147], v[20:23]
	ds_read_b128 v[136:139], v159 offset:12288
	ds_read_b128 v[140:143], v159 offset:14336
	ds_read_b128 v[144:147], v159 offset:16384
	ds_read_b128 v[148:151], v159 offset:18432
	ds_read_b128 v[152:155], v159 offset:20480
	s_waitcnt lgkmcnt(5)
	v_mfma_f32_16x16x32_bf16 v[24:27], v[204:207], v[164:167], v[24:27]
	v_mfma_f32_16x16x32_bf16 v[28:31], v[240:243], v[164:167], v[28:31]
	v_mfma_f32_16x16x32_bf16 v[32:35], v[204:207], v[168:171], v[32:35]
	v_mfma_f32_16x16x32_bf16 v[36:39], v[240:243], v[168:171], v[36:39]
	v_mfma_f32_16x16x32_bf16 v[40:43], v[204:207], v[172:175], v[40:43]
	v_mfma_f32_16x16x32_bf16 v[44:47], v[240:243], v[172:175], v[44:47]
	ds_read_b128 v[164:167], v159 offset:22528
	ds_read_b128 v[168:171], v159 offset:24576
	ds_read_b128 v[172:175], v159 offset:26624
	ds_read_b128 v[176:179], v159 offset:28672
	ds_read_b128 v[180:183], v159 offset:30720
	s_waitcnt lgkmcnt(5)
	v_mfma_f32_16x16x32_bf16 v[48:51], v[204:207], v[136:139], v[48:51]
	v_mfma_f32_16x16x32_bf16 v[52:55], v[240:243], v[136:139], v[52:55]
	v_mfma_f32_16x16x32_bf16 v[56:59], v[204:207], v[140:143], v[56:59]
	v_mfma_f32_16x16x32_bf16 v[60:63], v[240:243], v[140:143], v[60:63]
	v_mfma_f32_16x16x32_bf16 v[64:67], v[204:207], v[144:147], v[64:67]
	v_mfma_f32_16x16x32_bf16 v[68:71], v[240:243], v[144:147], v[68:71]
	v_mfma_f32_16x16x32_bf16 v[72:75], v[204:207], v[148:151], v[72:75]
	v_mfma_f32_16x16x32_bf16 v[76:79], v[240:243], v[148:151], v[76:79]
	v_mfma_f32_16x16x32_bf16 v[80:83], v[204:207], v[152:155], v[80:83]
	v_mfma_f32_16x16x32_bf16 v[84:87], v[240:243], v[152:155], v[84:87]
	s_waitcnt vmcnt(0) lgkmcnt(0)
	s_barrier
	s_cmp_ge_u32 s63, 14
	s_cbranch_scc1 .Lg2_ff1_nd16_1
	s_add_u32 s56, s56, 0x80
	s_addc_u32 s57, s57, 0
	s_add_u32 m0, s62, 0x8800
	s_add_u32 s4, s56, 0x0
	s_addc_u32 s5, s57, 0
	global_load_lds_dwordx4 v162, s[4:5]
	s_add_u32 m0, s62, 0x9800
	s_add_u32 s4, s56, 0x10000
	s_addc_u32 s5, s57, 0
	global_load_lds_dwordx4 v162, s[4:5]
	s_add_u32 m0, s62, 0xa800
	s_add_u32 s4, s56, 0x20000
	s_addc_u32 s5, s57, 0
	global_load_lds_dwordx4 v162, s[4:5]
	s_add_u32 m0, s62, 0xb800
	s_add_u32 s4, s56, 0x30000
	s_addc_u32 s5, s57, 0
	global_load_lds_dwordx4 v162, s[4:5]
	s_add_u32 m0, s62, 0xc800
	s_add_u32 s4, s56, 0x40000
	s_addc_u32 s5, s57, 0
	global_load_lds_dwordx4 v162, s[4:5]
	s_add_u32 m0, s62, 0xd800
	s_add_u32 s4, s56, 0x50000
	s_addc_u32 s5, s57, 0
	global_load_lds_dwordx4 v162, s[4:5]
	s_add_u32 m0, s62, 0xe800
	s_add_u32 s4, s56, 0x60000
	s_addc_u32 s5, s57, 0
	global_load_lds_dwordx4 v162, s[4:5]
	s_add_u32 m0, s62, 0xf800
	s_add_u32 s4, s56, 0x70000
	s_addc_u32 s5, s57, 0
	global_load_lds_dwordx4 v162, s[4:5]
	ds_read_b128 v[136:139], v156 offset:0
	ds_read_b128 v[140:143], v156 offset:2048
	ds_read_b128 v[144:147], v156 offset:4096
	ds_read_b128 v[148:151], v156 offset:6144
.Lg2_ff1_nd16_1:
	v_mfma_f32_16x16x32_bf16 v[88:91], v[204:207], v[164:167], v[88:91]
	v_mfma_f32_16x16x32_bf16 v[92:95], v[240:243], v[164:167], v[92:95]
	v_mfma_f32_16x16x32_bf16 v[96:99], v[204:207], v[168:171], v[96:99]
	v_mfma_f32_16x16x32_bf16 v[100:103], v[240:243], v[168:171], v[100:103]
	v_mfma_f32_16x16x32_bf16 v[104:107], v[204:207], v[172:175], v[104:107]
	v_mfma_f32_16x16x32_bf16 v[108:111], v[240:243], v[172:175], v[108:111]
	v_mfma_f32_16x16x32_bf16 v[112:115], v[204:207], v[176:179], v[112:115]
	v_mfma_f32_16x16x32_bf16 v[116:119], v[240:243], v[176:179], v[116:119]
	v_mfma_f32_16x16x32_bf16 v[120:123], v[204:207], v[180:183], v[120:123]
	v_mfma_f32_16x16x32_bf16 v[124:127], v[240:243], v[180:183], v[124:127]
	s_add_i32 s63, s63, 2
	s_cmp_lt_u32 s63, 16
	s_cbranch_scc1 .Lg2_ff1_loop16
	s_branch .Lg2_ff1_episel

.Lg2_up_loop17:
	s_add_u32 s58, s58, 0x800
	s_addc_u32 s59, s59, 0
	global_load_dwordx4 v[200:203], v160, s[58:59] offset:0
	global_load_dwordx4 v[204:207], v160, s[58:59] offset:1024
	global_load_dwordx4 v[208:211], v161, s[58:59] offset:0
	global_load_dwordx4 v[240:243], v161, s[58:59] offset:1024
	ds_read_b128 v[164:167], v156 offset:8192
	ds_read_b128 v[168:171], v156 offset:10240
	ds_read_b128 v[172:175], v156 offset:12288
	ds_read_b128 v[176:179], v156 offset:14336
	s_waitcnt lgkmcnt(4)
	v_mfma_f32_16x16x32_bf16 v[0:3], v[184:187], v[136:139], v[0:3]
	v_mfma_f32_16x16x32_bf16 v[4:7], v[192:195], v[136:139], v[4:7]
	v_mfma_f32_16x16x32_bf16 v[8:11], v[184:187], v[140:143], v[8:11]
	v_mfma_f32_16x16x32_bf16 v[12:15], v[192:195], v[140:143], v[12:15]
	v_mfma_f32_16x16x32_bf16 v[16:19], v[184:187], v[144:147], v[16:19]
	v_mfma_f32_16x16x32_bf16 v[20:23], v[192:195], v[144:147], v[20:23]
	v_mfma_f32_16x16x32_bf16 v[24:27], v[184:187], v[148:151], v[24:27]
	v_mfma_f32_16x16x32_bf16 v[28:31], v[192:195], v[148:151], v[28:31]
	ds_read_b128 v[136:139], v156 offset:16384
	ds_read_b128 v[140:143], v156 offset:18432
	ds_read_b128 v[144:147], v156 offset:20480
	ds_read_b128 v[148:151], v156 offset:22528
	s_waitcnt lgkmcnt(4)
	v_mfma_f32_16x16x32_bf16 v[32:35], v[184:187], v[164:167], v[32:35]
	v_mfma_f32_16x16x32_bf16 v[36:39], v[192:195], v[164:167], v[36:39]
	v_mfma_f32_16x16x32_bf16 v[40:43], v[184:187], v[168:171], v[40:43]
	v_mfma_f32_16x16x32_bf16 v[44:47], v[192:195], v[168:171], v[44:47]
	v_mfma_f32_16x16x32_bf16 v[48:51], v[184:187], v[172:175], v[48:51]
	v_mfma_f32_16x16x32_bf16 v[52:55], v[192:195], v[172:175], v[52:55]
	v_mfma_f32_16x16x32_bf16 v[56:59], v[184:187], v[176:179], v[56:59]
	v_mfma_f32_16x16x32_bf16 v[60:63], v[192:195], v[176:179], v[60:63]
	ds_read_b128 v[164:167], v156 offset:24576
	ds_read_b128 v[168:171], v156 offset:26624
	ds_read_b128 v[172:175], v156 offset:28672
	ds_read_b128 v[176:179], v156 offset:30720
	ds_read_b128 v[180:183], v156 offset:32768
	s_waitcnt lgkmcnt(5)
	v_mfma_f32_16x16x32_bf16 v[64:67], v[184:187], v[136:139], v[64:67]
	v_mfma_f32_16x16x32_bf16 v[68:71], v[192:195], v[136:139], v[68:71]
	v_mfma_f32_16x16x32_bf16 v[72:75], v[184:187], v[140:143], v[72:75]
	v_mfma_f32_16x16x32_bf16 v[76:79], v[192:195], v[140:143], v[76:79]
	v_mfma_f32_16x16x32_bf16 v[80:83], v[184:187], v[144:147], v[80:83]
	v_mfma_f32_16x16x32_bf16 v[84:87], v[192:195], v[144:147], v[84:87]
	v_mfma_f32_16x16x32_bf16 v[88:91], v[184:187], v[148:151], v[88:91]
	v_mfma_f32_16x16x32_bf16 v[92:95], v[192:195], v[148:151], v[92:95]
	ds_read_b128 v[136:139], v157 offset:0
	ds_read_b128 v[140:143], v157 offset:2048
	ds_read_b128 v[144:147], v157 offset:4096
	s_waitcnt lgkmcnt(3)
	v_mfma_f32_16x16x32_bf16 v[96:99], v[184:187], v[164:167], v[96:99]
	v_mfma_f32_16x16x32_bf16 v[100:103], v[192:195], v[164:167], v[100:103]
	v_mfma_f32_16x16x32_bf16 v[104:107], v[184:187], v[168:171], v[104:107]
	v_mfma_f32_16x16x32_bf16 v[108:111], v[192:195], v[168:171], v[108:111]
	v_mfma_f32_16x16x32_bf16 v[112:115], v[184:187], v[172:175], v[112:115]
	v_mfma_f32_16x16x32_bf16 v[116:119], v[192:195], v[172:175], v[116:119]
	v_mfma_f32_16x16x32_bf16 v[120:123], v[184:187], v[176:179], v[120:123]
	v_mfma_f32_16x16x32_bf16 v[124:127], v[192:195], v[176:179], v[124:127]
	v_mfma_f32_16x16x32_bf16 v[128:131], v[184:187], v[180:183], v[128:131]
	v_mfma_f32_16x16x32_bf16 v[132:135], v[192:195], v[180:183], v[132:135]
	ds_read_b128 v[164:167], v157 offset:6144
	ds_read_b128 v[168:171], v157 offset:8192
	ds_read_b128 v[172:175], v157 offset:10240
	ds_read_b128 v[176:179], v157 offset:12288
	s_waitcnt lgkmcnt(4)
	v_mfma_f32_16x16x32_bf16 v[0:3], v[188:191], v[136:139], v[0:3]
	v_mfma_f32_16x16x32_bf16 v[4:7], v[196:199], v[136:139], v[4:7]
	v_mfma_f32_16x16x32_bf16 v[8:11], v[188:191], v[140:143], v[8:11]
	v_mfma_f32_16x16x32_bf16 v[12:15], v[196:199], v[140:143], v[12:15]
	v_mfma_f32_16x16x32_bf16 v[16:19], v[188:191], v[144:147], v[16:19]
	v_mfma_f32_16x16x32_bf16 v[20:23], v[196:199], v[144:147], v[20:23]
	ds_read_b128 v[136:139], v157 offset:14336
	ds_read_b128 v[140:143], v157 offset:16384
	ds_read_b128 v[144:147], v157 offset:18432
	ds_read_b128 v[148:151], v157 offset:20480
	ds_read_b128 v[152:155], v157 offset:22528
	s_waitcnt lgkmcnt(5)
	v_mfma_f32_16x16x32_bf16 v[24:27], v[188:191], v[164:167], v[24:27]
	v_mfma_f32_16x16x32_bf16 v[28:31], v[196:199], v[164:167], v[28:31]
	v_mfma_f32_16x16x32_bf16 v[32:35], v[188:191], v[168:171], v[32:35]
	v_mfma_f32_16x16x32_bf16 v[36:39], v[196:199], v[168:171], v[36:39]
	v_mfma_f32_16x16x32_bf16 v[40:43], v[188:191], v[172:175], v[40:43]
	v_mfma_f32_16x16x32_bf16 v[44:47], v[196:199], v[172:175], v[44:47]
	v_mfma_f32_16x16x32_bf16 v[48:51], v[188:191], v[176:179], v[48:51]
	v_mfma_f32_16x16x32_bf16 v[52:55], v[196:199], v[176:179], v[52:55]
	ds_read_b128 v[164:167], v157 offset:24576
	ds_read_b128 v[168:171], v157 offset:26624
	ds_read_b128 v[172:175], v157 offset:28672
	ds_read_b128 v[176:179], v157 offset:30720
	ds_read_b128 v[180:183], v157 offset:32768
	s_waitcnt lgkmcnt(5)
	v_mfma_f32_16x16x32_bf16 v[56:59], v[188:191], v[136:139], v[56:59]
	v_mfma_f32_16x16x32_bf16 v[60:63], v[196:199], v[136:139], v[60:63]
	v_mfma_f32_16x16x32_bf16 v[64:67], v[188:191], v[140:143], v[64:67]
	v_mfma_f32_16x16x32_bf16 v[68:71], v[196:199], v[140:143], v[68:71]
	v_mfma_f32_16x16x32_bf16 v[72:75], v[188:191], v[144:147], v[72:75]
	v_mfma_f32_16x16x32_bf16 v[76:79], v[196:199], v[144:147], v[76:79]
	v_mfma_f32_16x16x32_bf16 v[80:83], v[188:191], v[148:151], v[80:83]
	v_mfma_f32_16x16x32_bf16 v[84:87], v[196:199], v[148:151], v[84:87]
	v_mfma_f32_16x16x32_bf16 v[88:91], v[188:191], v[152:155], v[88:91]
	v_mfma_f32_16x16x32_bf16 v[92:95], v[196:199], v[152:155], v[92:95]
	s_waitcnt vmcnt(0) lgkmcnt(0)
	s_barrier
	s_cmp_ge_u32 s63, 2
	s_cbranch_scc1 .Lg2_up_nd17_0
	s_add_u32 s56, s56, 0x80
	s_addc_u32 s57, s57, 0
	s_add_u32 m0, s62, 0x0
	s_add_u32 s4, s56, 0x0
	s_addc_u32 s5, s57, 0
	global_load_lds_dwordx4 v162, s[4:5]
	s_add_u32 m0, s62, 0x1000
	s_add_u32 s4, s56, 0x72000
	s_addc_u32 s5, s57, 0
	global_load_lds_dwordx4 v162, s[4:5]
	s_add_u32 m0, s62, 0x2000
	s_add_u32 s4, s56, 0xe4000
	s_addc_u32 s5, s57, 0
	global_load_lds_dwordx4 v162, s[4:5]
	s_add_u32 m0, s62, 0x3000
	s_add_u32 s4, s56, 0x156000
	s_addc_u32 s5, s57, 0
	global_load_lds_dwordx4 v162, s[4:5]
	s_add_u32 m0, s62, 0x4000
	s_add_u32 s4, s56, 0x1c8000
	s_addc_u32 s5, s57, 0
	global_load_lds_dwordx4 v162, s[4:5]
	s_add_u32 m0, s62, 0x5000
	s_add_u32 s4, s56, 0x23a000
	s_addc_u32 s5, s57, 0
	global_load_lds_dwordx4 v162, s[4:5]
	s_add_u32 m0, s62, 0x6000
	s_add_u32 s4, s56, 0x2ac000
	s_addc_u32 s5, s57, 0
	global_load_lds_dwordx4 v162, s[4:5]
	s_add_u32 m0, s62, 0x7000
	s_add_u32 s4, s56, 0x31e000
	s_addc_u32 s5, s57, 0
	global_load_lds_dwordx4 v162, s[4:5]
	s_cmp_gt_u32 s70, 1
	s_cbranch_scc1 .Lg2_up_nodma_2
	s_add_u32 m0, s62, 0x8000
	s_add_u32 s4, s56, 0x390000
	s_addc_u32 s5, s57, 0
	global_load_lds_dwordx4 v162, s[4:5]

.Lg2_up_nb17_1:
	ds_read_b128 v[164:167], v158 offset:8192
	ds_read_b128 v[168:171], v158 offset:10240
	ds_read_b128 v[172:175], v158 offset:12288
	ds_read_b128 v[176:179], v158 offset:14336
	s_waitcnt lgkmcnt(4)
	v_mfma_f32_16x16x32_bf16 v[0:3], v[200:203], v[136:139], v[0:3]
	v_mfma_f32_16x16x32_bf16 v[4:7], v[208:211], v[136:139], v[4:7]
	v_mfma_f32_16x16x32_bf16 v[8:11], v[200:203], v[140:143], v[8:11]
	v_mfma_f32_16x16x32_bf16 v[12:15], v[208:211], v[140:143], v[12:15]
	v_mfma_f32_16x16x32_bf16 v[16:19], v[200:203], v[144:147], v[16:19]
	v_mfma_f32_16x16x32_bf16 v[20:23], v[208:211], v[144:147], v[20:23]
	v_mfma_f32_16x16x32_bf16 v[24:27], v[200:203], v[148:151], v[24:27]
	v_mfma_f32_16x16x32_bf16 v[28:31], v[208:211], v[148:151], v[28:31]
	ds_read_b128 v[136:139], v158 offset:16384
	ds_read_b128 v[140:143], v158 offset:18432
	ds_read_b128 v[144:147], v158 offset:20480
	ds_read_b128 v[148:151], v158 offset:22528
	s_waitcnt lgkmcnt(4)
	v_mfma_f32_16x16x32_bf16 v[32:35], v[200:203], v[164:167], v[32:35]
	v_mfma_f32_16x16x32_bf16 v[36:39], v[208:211], v[164:167], v[36:39]
	v_mfma_f32_16x16x32_bf16 v[40:43], v[200:203], v[168:171], v[40:43]
	v_mfma_f32_16x16x32_bf16 v[44:47], v[208:211], v[168:171], v[44:47]
	v_mfma_f32_16x16x32_bf16 v[48:51], v[200:203], v[172:175], v[48:51]
	v_mfma_f32_16x16x32_bf16 v[52:55], v[208:211], v[172:175], v[52:55]
	v_mfma_f32_16x16x32_bf16 v[56:59], v[200:203], v[176:179], v[56:59]
	v_mfma_f32_16x16x32_bf16 v[60:63], v[208:211], v[176:179], v[60:63]
	ds_read_b128 v[164:167], v158 offset:24576
	ds_read_b128 v[168:171], v158 offset:26624
	ds_read_b128 v[172:175], v158 offset:28672
	ds_read_b128 v[176:179], v158 offset:30720
	ds_read_b128 v[180:183], v158 offset:32768
	s_waitcnt lgkmcnt(5)
	v_mfma_f32_16x16x32_bf16 v[64:67], v[200:203], v[136:139], v[64:67]
	v_mfma_f32_16x16x32_bf16 v[68:71], v[208:211], v[136:139], v[68:71]
	v_mfma_f32_16x16x32_bf16 v[72:75], v[200:203], v[140:143], v[72:75]
	v_mfma_f32_16x16x32_bf16 v[76:79], v[208:211], v[140:143], v[76:79]
	v_mfma_f32_16x16x32_bf16 v[80:83], v[200:203], v[144:147], v[80:83]
	v_mfma_f32_16x16x32_bf16 v[84:87], v[208:211], v[144:147], v[84:87]
	v_mfma_f32_16x16x32_bf16 v[88:91], v[200:203], v[148:151], v[88:91]
	v_mfma_f32_16x16x32_bf16 v[92:95], v[208:211], v[148:151], v[92:95]
	ds_read_b128 v[136:139], v159 offset:0
	ds_read_b128 v[140:143], v159 offset:2048
	ds_read_b128 v[144:147], v159 offset:4096
	s_waitcnt lgkmcnt(3)
	v_mfma_f32_16x16x32_bf16 v[96:99], v[200:203], v[164:167], v[96:99]
	v_mfma_f32_16x16x32_bf16 v[100:103], v[208:211], v[164:167], v[100:103]
	v_mfma_f32_16x16x32_bf16 v[104:107], v[200:203], v[168:171], v[104:107]
	v_mfma_f32_16x16x32_bf16 v[108:111], v[208:211], v[168:171], v[108:111]
	v_mfma_f32_16x16x32_bf16 v[112:115], v[200:203], v[172:175], v[112:115]
	v_mfma_f32_16x16x32_bf16 v[116:119], v[208:211], v[172:175], v[116:119]
	v_mfma_f32_16x16x32_bf16 v[120:123], v[200:203], v[176:179], v[120:123]
	v_mfma_f32_16x16x32_bf16 v[124:127], v[208:211], v[176:179], v[124:127]
	v_mfma_f32_16x16x32_bf16 v[128:131], v[200:203], v[180:183], v[128:131]
	v_mfma_f32_16x16x32_bf16 v[132:135], v[208:211], v[180:183], v[132:135]
	ds_read_b128 v[164:167], v159 offset:6144
	ds_read_b128 v[168:171], v159 offset:8192
	ds_read_b128 v[172:175], v159 offset:10240
	ds_read_b128 v[176:179], v159 offset:12288
	s_waitcnt lgkmcnt(4)
	v_mfma_f32_16x16x32_bf16 v[0:3], v[204:207], v[136:139], v[0:3]
	v_mfma_f32_16x16x32_bf16 v[4:7], v[240:243], v[136:139], v[4:7]
	v_mfma_f32_16x16x32_bf16 v[8:11], v[204:207], v[140:143], v[8:11]
	v_mfma_f32_16x16x32_bf16 v[12:15], v[240:243], v[140:143], v[12:15]
	v_mfma_f32_16x16x32_bf16 v[16:19], v[204:207], v[144:147], v[16:19]
	v_mfma_f32_16x16x32_bf16 v[20:23], v[240:243], v[144:147], v[20:23]
	ds_read_b128 v[136:139], v159 offset:14336
	ds_read_b128 v[140:143], v159 offset:16384
	ds_read_b128 v[144:147], v159 offset:18432
	ds_read_b128 v[148:151], v159 offset:20480
	ds_read_b128 v[152:155], v159 offset:22528
	s_waitcnt lgkmcnt(5)
	v_mfma_f32_16x16x32_bf16 v[24:27], v[204:207], v[164:167], v[24:27]
	v_mfma_f32_16x16x32_bf16 v[28:31], v[240:243], v[164:167], v[28:31]
	v_mfma_f32_16x16x32_bf16 v[32:35], v[204:207], v[168:171], v[32:35]
	v_mfma_f32_16x16x32_bf16 v[36:39], v[240:243], v[168:171], v[36:39]
	v_mfma_f32_16x16x32_bf16 v[40:43], v[204:207], v[172:175], v[40:43]
	v_mfma_f32_16x16x32_bf16 v[44:47], v[240:243], v[172:175], v[44:47]
	v_mfma_f32_16x16x32_bf16 v[48:51], v[204:207], v[176:179], v[48:51]
	v_mfma_f32_16x16x32_bf16 v[52:55], v[240:243], v[176:179], v[52:55]
	ds_read_b128 v[164:167], v159 offset:24576
	ds_read_b128 v[168:171], v159 offset:26624
	ds_read_b128 v[172:175], v159 offset:28672
	ds_read_b128 v[176:179], v159 offset:30720
	ds_read_b128 v[180:183], v159 offset:32768
	s_waitcnt lgkmcnt(5)
	v_mfma_f32_16x16x32_bf16 v[56:59], v[204:207], v[136:139], v[56:59]
	v_mfma_f32_16x16x32_bf16 v[60:63], v[240:243], v[136:139], v[60:63]
	v_mfma_f32_16x16x32_bf16 v[64:67], v[204:207], v[140:143], v[64:67]
	v_mfma_f32_16x16x32_bf16 v[68:71], v[240:243], v[140:143], v[68:71]
	v_mfma_f32_16x16x32_bf16 v[72:75], v[204:207], v[144:147], v[72:75]
	v_mfma_f32_16x16x32_bf16 v[76:79], v[240:243], v[144:147], v[76:79]
	v_mfma_f32_16x16x32_bf16 v[80:83], v[204:207], v[148:151], v[80:83]
	v_mfma_f32_16x16x32_bf16 v[84:87], v[240:243], v[148:151], v[84:87]
	v_mfma_f32_16x16x32_bf16 v[88:91], v[204:207], v[152:155], v[88:91]
	v_mfma_f32_16x16x32_bf16 v[92:95], v[240:243], v[152:155], v[92:95]
	s_waitcnt vmcnt(0) lgkmcnt(0)
	s_barrier
	s_cmp_ge_u32 s63, 2
	s_cbranch_scc1 .Lg2_up_nd17_1
	s_add_u32 s56, s56, 0x80
	s_addc_u32 s57, s57, 0
	s_add_u32 m0, s62, 0x8800
	s_add_u32 s4, s56, 0x0
	s_addc_u32 s5, s57, 0
	global_load_lds_dwordx4 v162, s[4:5]
	s_add_u32 m0, s62, 0x9800
	s_add_u32 s4, s56, 0x72000
	s_addc_u32 s5, s57, 0
	global_load_lds_dwordx4 v162, s[4:5]
	s_add_u32 m0, s62, 0xa800
	s_add_u32 s4, s56, 0xe4000
	s_addc_u32 s5, s57, 0
	global_load_lds_dwordx4 v162, s[4:5]
	s_add_u32 m0, s62, 0xb800
	s_add_u32 s4, s56, 0x156000
	s_addc_u32 s5, s57, 0
	global_load_lds_dwordx4 v162, s[4:5]
	s_add_u32 m0, s62, 0xc800
	s_add_u32 s4, s56, 0x1c8000
	s_addc_u32 s5, s57, 0
	global_load_lds_dwordx4 v162, s[4:5]
	s_add_u32 m0, s62, 0xd800
	s_add_u32 s4, s56, 0x23a000
	s_addc_u32 s5, s57, 0
	global_load_lds_dwordx4 v162, s[4:5]
	s_add_u32 m0, s62, 0xe800
	s_add_u32 s4, s56, 0x2ac000
	s_addc_u32 s5, s57, 0
	global_load_lds_dwordx4 v162, s[4:5]
	s_add_u32 m0, s62, 0xf800
	s_add_u32 s4, s56, 0x31e000
	s_addc_u32 s5, s57, 0
	global_load_lds_dwordx4 v162, s[4:5]
	s_cmp_gt_u32 s70, 1
	s_cbranch_scc1 .Lg2_up_nodma_3
	s_add_u32 m0, s62, 0x10800
	s_add_u32 s4, s56, 0x390000
	s_addc_u32 s5, s57, 0
	global_load_lds_dwordx4 v162, s[4:5]

.Lg2_up_loop16:
	s_add_u32 s58, s58, 0x800
	s_addc_u32 s59, s59, 0
	global_load_dwordx4 v[200:203], v160, s[58:59] offset:0
	global_load_dwordx4 v[204:207], v160, s[58:59] offset:1024
	global_load_dwordx4 v[208:211], v161, s[58:59] offset:0
	global_load_dwordx4 v[240:243], v161, s[58:59] offset:1024
	ds_read_b128 v[164:167], v156 offset:8192
	ds_read_b128 v[168:171], v156 offset:10240
	ds_read_b128 v[172:175], v156 offset:12288
	ds_read_b128 v[176:179], v156 offset:14336
	s_waitcnt lgkmcnt(4)
	v_mfma_f32_16x16x32_bf16 v[0:3], v[184:187], v[136:139], v[0:3]
	v_mfma_f32_16x16x32_bf16 v[4:7], v[192:195], v[136:139], v[4:7]
	v_mfma_f32_16x16x32_bf16 v[8:11], v[184:187], v[140:143], v[8:11]
	v_mfma_f32_16x16x32_bf16 v[12:15], v[192:195], v[140:143], v[12:15]
	v_mfma_f32_16x16x32_bf16 v[16:19], v[184:187], v[144:147], v[16:19]
	v_mfma_f32_16x16x32_bf16 v[20:23], v[192:195], v[144:147], v[20:23]
	v_mfma_f32_16x16x32_bf16 v[24:27], v[184:187], v[148:151], v[24:27]
	v_mfma_f32_16x16x32_bf16 v[28:31], v[192:195], v[148:151], v[28:31]
	ds_read_b128 v[136:139], v156 offset:16384
	ds_read_b128 v[140:143], v156 offset:18432
	ds_read_b128 v[144:147], v156 offset:20480
	ds_read_b128 v[148:151], v156 offset:22528
	s_waitcnt lgkmcnt(4)
	v_mfma_f32_16x16x32_bf16 v[32:35], v[184:187], v[164:167], v[32:35]
	v_mfma_f32_16x16x32_bf16 v[36:39], v[192:195], v[164:167], v[36:39]
	v_mfma_f32_16x16x32_bf16 v[40:43], v[184:187], v[168:171], v[40:43]
	v_mfma_f32_16x16x32_bf16 v[44:47], v[192:195], v[168:171], v[44:47]
	v_mfma_f32_16x16x32_bf16 v[48:51], v[184:187], v[172:175], v[48:51]
	v_mfma_f32_16x16x32_bf16 v[52:55], v[192:195], v[172:175], v[52:55]
	v_mfma_f32_16x16x32_bf16 v[56:59], v[184:187], v[176:179], v[56:59]
	v_mfma_f32_16x16x32_bf16 v[60:63], v[192:195], v[176:179], v[60:63]
	ds_read_b128 v[164:167], v156 offset:24576
	ds_read_b128 v[168:171], v156 offset:26624
	ds_read_b128 v[172:175], v156 offset:28672
	ds_read_b128 v[176:179], v156 offset:30720
	s_waitcnt lgkmcnt(4)
	v_mfma_f32_16x16x32_bf16 v[64:67], v[184:187], v[136:139], v[64:67]
	v_mfma_f32_16x16x32_bf16 v[68:71], v[192:195], v[136:139], v[68:71]
	v_mfma_f32_16x16x32_bf16 v[72:75], v[184:187], v[140:143], v[72:75]
	v_mfma_f32_16x16x32_bf16 v[76:79], v[192:195], v[140:143], v[76:79]
	v_mfma_f32_16x16x32_bf16 v[80:83], v[184:187], v[144:147], v[80:83]
	v_mfma_f32_16x16x32_bf16 v[84:87], v[192:195], v[144:147], v[84:87]
	v_mfma_f32_16x16x32_bf16 v[88:91], v[184:187], v[148:151], v[88:91]
	v_mfma_f32_16x16x32_bf16 v[92:95], v[192:195], v[148:151], v[92:95]
	ds_read_b128 v[136:139], v157 offset:0
	ds_read_b128 v[140:143], v157 offset:2048
	ds_read_b128 v[144:147], v157 offset:4096
	s_waitcnt lgkmcnt(3)
	v_mfma_f32_16x16x32_bf16 v[96:99], v[184:187], v[164:167], v[96:99]
	v_mfma_f32_16x16x32_bf16 v[100:103], v[192:195], v[164:167], v[100:103]
	v_mfma_f32_16x16x32_bf16 v[104:107], v[184:187], v[168:171], v[104:107]
	v_mfma_f32_16x16x32_bf16 v[108:111], v[192:195], v[168:171], v[108:111]
	v_mfma_f32_16x16x32_bf16 v[112:115], v[184:187], v[172:175], v[112:115]
	v_mfma_f32_16x16x32_bf16 v[116:119], v[192:195], v[172:175], v[116:119]
	v_mfma_f32_16x16x32_bf16 v[120:123], v[184:187], v[176:179], v[120:123]
	v_mfma_f32_16x16x32_bf16 v[124:127], v[192:195], v[176:179], v[124:127]
	ds_read_b128 v[164:167], v157 offset:6144
	ds_read_b128 v[168:171], v157 offset:8192
	ds_read_b128 v[172:175], v157 offset:10240
	s_waitcnt lgkmcnt(3)
	v_mfma_f32_16x16x32_bf16 v[0:3], v[188:191], v[136:139], v[0:3]
	v_mfma_f32_16x16x32_bf16 v[4:7], v[196:199], v[136:139], v[4:7]
	v_mfma_f32_16x16x32_bf16 v[8:11], v[188:191], v[140:143], v[8:11]
	v_mfma_f32_16x16x32_bf16 v[12:15], v[196:199], v[140:143], v[12:15]
	v_mfma_f32_16x16x32_bf16 v[16:19], v[188:191], v[144:147], v[16:19]
	v_mfma_f32_16x16x32_bf16 v[20:23], v[196:199], v[144:147], v[20:23]
	ds_read_b128 v[136:139], v157 offset:12288
	ds_read_b128 v[140:143], v157 offset:14336
	ds_read_b128 v[144:147], v157 offset:16384
	ds_read_b128 v[148:151], v157 offset:18432
	ds_read_b128 v[152:155], v157 offset:20480
	s_waitcnt lgkmcnt(5)
	v_mfma_f32_16x16x32_bf16 v[24:27], v[188:191], v[164:167], v[24:27]
	v_mfma_f32_16x16x32_bf16 v[28:31], v[196:199], v[164:167], v[28:31]
	v_mfma_f32_16x16x32_bf16 v[32:35], v[188:191], v[168:171], v[32:35]
	v_mfma_f32_16x16x32_bf16 v[36:39], v[196:199], v[168:171], v[36:39]
	v_mfma_f32_16x16x32_bf16 v[40:43], v[188:191], v[172:175], v[40:43]
	v_mfma_f32_16x16x32_bf16 v[44:47], v[196:199], v[172:175], v[44:47]
	ds_read_b128 v[164:167], v157 offset:22528
	ds_read_b128 v[168:171], v157 offset:24576
	ds_read_b128 v[172:175], v157 offset:26624
	ds_read_b128 v[176:179], v157 offset:28672
	ds_read_b128 v[180:183], v157 offset:30720
	s_waitcnt lgkmcnt(5)
	v_mfma_f32_16x16x32_bf16 v[48:51], v[188:191], v[136:139], v[48:51]
	v_mfma_f32_16x16x32_bf16 v[52:55], v[196:199], v[136:139], v[52:55]
	v_mfma_f32_16x16x32_bf16 v[56:59], v[188:191], v[140:143], v[56:59]
	v_mfma_f32_16x16x32_bf16 v[60:63], v[196:199], v[140:143], v[60:63]
	v_mfma_f32_16x16x32_bf16 v[64:67], v[188:191], v[144:147], v[64:67]
	v_mfma_f32_16x16x32_bf16 v[68:71], v[196:199], v[144:147], v[68:71]
	v_mfma_f32_16x16x32_bf16 v[72:75], v[188:191], v[148:151], v[72:75]
	v_mfma_f32_16x16x32_bf16 v[76:79], v[196:199], v[148:151], v[76:79]
	v_mfma_f32_16x16x32_bf16 v[80:83], v[188:191], v[152:155], v[80:83]
	v_mfma_f32_16x16x32_bf16 v[84:87], v[196:199], v[152:155], v[84:87]
	s_waitcnt vmcnt(0) lgkmcnt(0)
	s_barrier
	s_cmp_ge_u32 s63, 2
	s_cbranch_scc1 .Lg2_up_nd16_0
	s_add_u32 s56, s56, 0x80
	s_addc_u32 s57, s57, 0
	s_add_u32 m0, s62, 0x0
	s_add_u32 s4, s56, 0x0
	s_addc_u32 s5, s57, 0
	global_load_lds_dwordx4 v162, s[4:5]
	s_add_u32 m0, s62, 0x1000
	s_add_u32 s4, s56, 0x72000
	s_addc_u32 s5, s57, 0
	global_load_lds_dwordx4 v162, s[4:5]
	s_add_u32 m0, s62, 0x2000
	s_add_u32 s4, s56, 0xe4000
	s_addc_u32 s5, s57, 0
	global_load_lds_dwordx4 v162, s[4:5]
	s_add_u32 m0, s62, 0x3000
	s_add_u32 s4, s56, 0x156000
	s_addc_u32 s5, s57, 0
	global_load_lds_dwordx4 v162, s[4:5]
	s_add_u32 m0, s62, 0x4000
	s_add_u32 s4, s56, 0x1c8000
	s_addc_u32 s5, s57, 0
	global_load_lds_dwordx4 v162, s[4:5]
	s_add_u32 m0, s62, 0x5000
	s_add_u32 s4, s56, 0x23a000
	s_addc_u32 s5, s57, 0
	global_load_lds_dwordx4 v162, s[4:5]
	s_add_u32 m0, s62, 0x6000
	s_add_u32 s4, s56, 0x2ac000
	s_addc_u32 s5, s57, 0
	global_load_lds_dwordx4 v162, s[4:5]
	s_add_u32 m0, s62, 0x7000
	s_add_u32 s4, s56, 0x31e000
	s_addc_u32 s5, s57, 0
	global_load_lds_dwordx4 v162, s[4:5]
.Lg2_up_nd16_0:
	ds_read_b128 v[136:139], v158 offset:0
	ds_read_b128 v[140:143], v158 offset:2048
	ds_read_b128 v[144:147], v158 offset:4096
	ds_read_b128 v[148:151], v158 offset:6144
	v_mfma_f32_16x16x32_bf16 v[88:91], v[188:191], v[164:167], v[88:91]
	v_mfma_f32_16x16x32_bf16 v[92:95], v[196:199], v[164:167], v[92:95]
	v_mfma_f32_16x16x32_bf16 v[96:99], v[188:191], v[168:171], v[96:99]
	v_mfma_f32_16x16x32_bf16 v[100:103], v[196:199], v[168:171], v[100:103]
	v_mfma_f32_16x16x32_bf16 v[104:107], v[188:191], v[172:175], v[104:107]
	v_mfma_f32_16x16x32_bf16 v[108:111], v[196:199], v[172:175], v[108:111]
	v_mfma_f32_16x16x32_bf16 v[112:115], v[188:191], v[176:179], v[112:115]
	v_mfma_f32_16x16x32_bf16 v[116:119], v[196:199], v[176:179], v[116:119]
	v_mfma_f32_16x16x32_bf16 v[120:123], v[188:191], v[180:183], v[120:123]
	v_mfma_f32_16x16x32_bf16 v[124:127], v[196:199], v[180:183], v[124:127]
	s_cmp_ge_u32 s63, 2
	s_cbranch_scc1 .Lg2_up_nb16_1
	s_add_u32 s58, s58, 0x800
	s_addc_u32 s59, s59, 0
	global_load_dwordx4 v[184:187], v160, s[58:59] offset:0
	global_load_dwordx4 v[188:191], v160, s[58:59] offset:1024
	global_load_dwordx4 v[192:195], v161, s[58:59] offset:0
	global_load_dwordx4 v[196:199], v161, s[58:59] offset:1024
.Lg2_up_nb16_1:
	ds_read_b128 v[164:167], v158 offset:8192
	ds_read_b128 v[168:171], v158 offset:10240
	ds_read_b128 v[172:175], v158 offset:12288
	ds_read_b128 v[176:179], v158 offset:14336
	s_waitcnt lgkmcnt(4)
	v_mfma_f32_16x16x32_bf16 v[0:3], v[200:203], v[136:139], v[0:3]
	v_mfma_f32_16x16x32_bf16 v[4:7], v[208:211], v[136:139], v[4:7]
	v_mfma_f32_16x16x32_bf16 v[8:11], v[200:203], v[140:143], v[8:11]
	v_mfma_f32_16x16x32_bf16 v[12:15], v[208:211], v[140:143], v[12:15]
	v_mfma_f32_16x16x32_bf16 v[16:19], v[200:203], v[144:147], v[16:19]
	v_mfma_f32_16x16x32_bf16 v[20:23], v[208:211], v[144:147], v[20:23]
	v_mfma_f32_16x16x32_bf16 v[24:27], v[200:203], v[148:151], v[24:27]
	v_mfma_f32_16x16x32_bf16 v[28:31], v[208:211], v[148:151], v[28:31]
	ds_read_b128 v[136:139], v158 offset:16384
	ds_read_b128 v[140:143], v158 offset:18432
	ds_read_b128 v[144:147], v158 offset:20480
	ds_read_b128 v[148:151], v158 offset:22528
	s_waitcnt lgkmcnt(4)
	v_mfma_f32_16x16x32_bf16 v[32:35], v[200:203], v[164:167], v[32:35]
	v_mfma_f32_16x16x32_bf16 v[36:39], v[208:211], v[164:167], v[36:39]
	v_mfma_f32_16x16x32_bf16 v[40:43], v[200:203], v[168:171], v[40:43]
	v_mfma_f32_16x16x32_bf16 v[44:47], v[208:211], v[168:171], v[44:47]
	v_mfma_f32_16x16x32_bf16 v[48:51], v[200:203], v[172:175], v[48:51]
	v_mfma_f32_16x16x32_bf16 v[52:55], v[208:211], v[172:175], v[52:55]
	v_mfma_f32_16x16x32_bf16 v[56:59], v[200:203], v[176:179], v[56:59]
	v_mfma_f32_16x16x32_bf16 v[60:63], v[208:211], v[176:179], v[60:63]
	ds_read_b128 v[164:167], v158 offset:24576
	ds_read_b128 v[168:171], v158 offset:26624
	ds_read_b128 v[172:175], v158 offset:28672
	ds_read_b128 v[176:179], v158 offset:30720
	s_waitcnt lgkmcnt(4)
	v_mfma_f32_16x16x32_bf16 v[64:67], v[200:203], v[136:139], v[64:67]
	v_mfma_f32_16x16x32_bf16 v[68:71], v[208:211], v[136:139], v[68:71]
	v_mfma_f32_16x16x32_bf16 v[72:75], v[200:203], v[140:143], v[72:75]
	v_mfma_f32_16x16x32_bf16 v[76:79], v[208:211], v[140:143], v[76:79]
	v_mfma_f32_16x16x32_bf16 v[80:83], v[200:203], v[144:147], v[80:83]
	v_mfma_f32_16x16x32_bf16 v[84:87], v[208:211], v[144:147], v[84:87]
	v_mfma_f32_16x16x32_bf16 v[88:91], v[200:203], v[148:151], v[88:91]
	v_mfma_f32_16x16x32_bf16 v[92:95], v[208:211], v[148:151], v[92:95]
	ds_read_b128 v[136:139], v159 offset:0
	ds_read_b128 v[140:143], v159 offset:2048
	ds_read_b128 v[144:147], v159 offset:4096
	s_waitcnt lgkmcnt(3)
	v_mfma_f32_16x16x32_bf16 v[96:99], v[200:203], v[164:167], v[96:99]
	v_mfma_f32_16x16x32_bf16 v[100:103], v[208:211], v[164:167], v[100:103]
	v_mfma_f32_16x16x32_bf16 v[104:107], v[200:203], v[168:171], v[104:107]
	v_mfma_f32_16x16x32_bf16 v[108:111], v[208:211], v[168:171], v[108:111]
	v_mfma_f32_16x16x32_bf16 v[112:115], v[200:203], v[172:175], v[112:115]
	v_mfma_f32_16x16x32_bf16 v[116:119], v[208:211], v[172:175], v[116:119]
	v_mfma_f32_16x16x32_bf16 v[120:123], v[200:203], v[176:179], v[120:123]
	v_mfma_f32_16x16x32_bf16 v[124:127], v[208:211], v[176:179], v[124:127]
	ds_read_b128 v[164:167], v159 offset:6144
	ds_read_b128 v[168:171], v159 offset:8192
	ds_read_b128 v[172:175], v159 offset:10240
	s_waitcnt lgkmcnt(3)
	v_mfma_f32_16x16x32_bf16 v[0:3], v[204:207], v[136:139], v[0:3]
	v_mfma_f32_16x16x32_bf16 v[4:7], v[240:243], v[136:139], v[4:7]
	v_mfma_f32_16x16x32_bf16 v[8:11], v[204:207], v[140:143], v[8:11]
	v_mfma_f32_16x16x32_bf16 v[12:15], v[240:243], v[140:143], v[12:15]
	v_mfma_f32_16x16x32_bf16 v[16:19], v[204:207], v[144:147], v[16:19]
	v_mfma_f32_16x16x32_bf16 v[20:23], v[240:243], v[144:147], v[20:23]
	ds_read_b128 v[136:139], v159 offset:12288
	ds_read_b128 v[140:143], v159 offset:14336
	ds_read_b128 v[144:147], v159 offset:16384
	ds_read_b128 v[148:151], v159 offset:18432
	ds_read_b128 v[152:155], v159 offset:20480
	s_waitcnt lgkmcnt(5)
	v_mfma_f32_16x16x32_bf16 v[24:27], v[204:207], v[164:167], v[24:27]
	v_mfma_f32_16x16x32_bf16 v[28:31], v[240:243], v[164:167], v[28:31]
	v_mfma_f32_16x16x32_bf16 v[32:35], v[204:207], v[168:171], v[32:35]
	v_mfma_f32_16x16x32_bf16 v[36:39], v[240:243], v[168:171], v[36:39]
	v_mfma_f32_16x16x32_bf16 v[40:43], v[204:207], v[172:175], v[40:43]
	v_mfma_f32_16x16x32_bf16 v[44:47], v[240:243], v[172:175], v[44:47]
	ds_read_b128 v[164:167], v159 offset:22528
	ds_read_b128 v[168:171], v159 offset:24576
	ds_read_b128 v[172:175], v159 offset:26624
	ds_read_b128 v[176:179], v159 offset:28672
	ds_read_b128 v[180:183], v159 offset:30720
	s_waitcnt lgkmcnt(5)
	v_mfma_f32_16x16x32_bf16 v[48:51], v[204:207], v[136:139], v[48:51]
	v_mfma_f32_16x16x32_bf16 v[52:55], v[240:243], v[136:139], v[52:55]
	v_mfma_f32_16x16x32_bf16 v[56:59], v[204:207], v[140:143], v[56:59]
	v_mfma_f32_16x16x32_bf16 v[60:63], v[240:243], v[140:143], v[60:63]
	v_mfma_f32_16x16x32_bf16 v[64:67], v[204:207], v[144:147], v[64:67]
	v_mfma_f32_16x16x32_bf16 v[68:71], v[240:243], v[144:147], v[68:71]
	v_mfma_f32_16x16x32_bf16 v[72:75], v[204:207], v[148:151], v[72:75]
	v_mfma_f32_16x16x32_bf16 v[76:79], v[240:243], v[148:151], v[76:79]
	v_mfma_f32_16x16x32_bf16 v[80:83], v[204:207], v[152:155], v[80:83]
	v_mfma_f32_16x16x32_bf16 v[84:87], v[240:243], v[152:155], v[84:87]
	s_waitcnt vmcnt(0) lgkmcnt(0)
	s_barrier
	s_cmp_ge_u32 s63, 2
	s_cbranch_scc1 .Lg2_up_nd16_1
	s_add_u32 s56, s56, 0x80
	s_addc_u32 s57, s57, 0
	s_add_u32 m0, s62, 0x8800
	s_add_u32 s4, s56, 0x0
	s_addc_u32 s5, s57, 0
	global_load_lds_dwordx4 v162, s[4:5]
	s_add_u32 m0, s62, 0x9800
	s_add_u32 s4, s56, 0x72000
	s_addc_u32 s5, s57, 0
	global_load_lds_dwordx4 v162, s[4:5]
	s_add_u32 m0, s62, 0xa800
	s_add_u32 s4, s56, 0xe4000
	s_addc_u32 s5, s57, 0
	global_load_lds_dwordx4 v162, s[4:5]
	s_add_u32 m0, s62, 0xb800
	s_add_u32 s4, s56, 0x156000
	s_addc_u32 s5, s57, 0
	global_load_lds_dwordx4 v162, s[4:5]
	s_add_u32 m0, s62, 0xc800
	s_add_u32 s4, s56, 0x1c8000
	s_addc_u32 s5, s57, 0
	global_load_lds_dwordx4 v162, s[4:5]
	s_add_u32 m0, s62, 0xd800
	s_add_u32 s4, s56, 0x23a000
	s_addc_u32 s5, s57, 0
	global_load_lds_dwordx4 v162, s[4:5]
	s_add_u32 m0, s62, 0xe800
	s_add_u32 s4, s56, 0x2ac000
	s_addc_u32 s5, s57, 0
	global_load_lds_dwordx4 v162, s[4:5]
	s_add_u32 m0, s62, 0xf800
	s_add_u32 s4, s56, 0x31e000
	s_addc_u32 s5, s57, 0
	global_load_lds_dwordx4 v162, s[4:5]
	ds_read_b128 v[136:139], v156 offset:0
	ds_read_b128 v[140:143], v156 offset:2048
	ds_read_b128 v[144:147], v156 offset:4096
	ds_read_b128 v[148:151], v156 offset:6144
.Lg2_up_nd16_1:
	v_mfma_f32_16x16x32_bf16 v[88:91], v[204:207], v[164:167], v[88:91]
	v_mfma_f32_16x16x32_bf16 v[92:95], v[240:243], v[164:167], v[92:95]
	v_mfma_f32_16x16x32_bf16 v[96:99], v[204:207], v[168:171], v[96:99]
	v_mfma_f32_16x16x32_bf16 v[100:103], v[240:243], v[168:171], v[100:103]
	v_mfma_f32_16x16x32_bf16 v[104:107], v[204:207], v[172:175], v[104:107]
	v_mfma_f32_16x16x32_bf16 v[108:111], v[240:243], v[172:175], v[108:111]
	v_mfma_f32_16x16x32_bf16 v[112:115], v[204:207], v[176:179], v[112:115]
	v_mfma_f32_16x16x32_bf16 v[116:119], v[240:243], v[176:179], v[116:119]
	v_mfma_f32_16x16x32_bf16 v[120:123], v[204:207], v[180:183], v[120:123]
	v_mfma_f32_16x16x32_bf16 v[124:127], v[240:243], v[180:183], v[124:127]
	s_add_i32 s63, s63, 2
	s_cmp_lt_u32 s63, 4
	s_cbranch_scc1 .Lg2_up_loop16
	s_branch .Lg2_up_episel
